# speedup vs baseline: 1.0410x; 1.0078x over previous
; DI float bflo(unsigned w) { return __uint_as_float(w << 16); }
; DI float bfhi(unsigned w) { return __uint_as_float(w & 0xffff0000u); }
; DI unsigned cvtpk(float lo, float hi) { unsigned r; asm volatile("v_cvt_pk_bf16_f32 %0, %1, %2" : "=v"(r) : "v"(lo), "v"(hi)); return r; }
; DI float sigmoidf_(float x) { return __builtin_amdgcn_rcpf(1.f + __expf(-x)); }
;     __device__ __forceinline__ void operator()(const f32x4 (&acc)[2][2][4][2], const Unit& u, int wr, int wc, int fr, int fq) const {
;     ...
;                 const int row = u.pm * BM + ai * HALF + wr * 64 + m * 16 + fr;
;                 const int colb = pn * BM + wc * 32 + 8 * fq;
;                 const unsigned goff = (unsigned)(row * LDP + C_GT + br * 1024 + colb), ooff = (unsigned)(row * 1024 + colb);
;                 const bf16_t* gp = proj + goff;
;                 bf16_t* op = out + ooff;
;                 __builtin_amdgcn_sched_barrier(0);
; #pragma unroll
;                 for (int bj = 0; bj < 2; ++bj) {
;                     const u32x4 g = *(const u32x4*)(gp + bj * HALF);
;                     f32x4 v0 = acc[ai][bj][m][0], v1 = acc[ai][bj][m][1];
;                     v0[0] *= sigmoidf_(bflo(g[0])); v0[1] *= sigmoidf_(bfhi(g[0])); v0[2] *= sigmoidf_(bflo(g[1])); v0[3] *= sigmoidf_(bfhi(g[1]));
;                     v1[0] *= sigmoidf_(bflo(g[2])); v1[1] *= sigmoidf_(bfhi(g[2])); v1[2] *= sigmoidf_(bflo(g[3])); v1[3] *= sigmoidf_(bfhi(g[3]));
;                     if (br > 0) {
;                         const u32x4 o = *(const u32x4*)(op + bj * HALF);
;                         v0[0] += bflo(o[0]); v0[1] += bfhi(o[0]); v0[2] += bflo(o[1]); v0[3] += bfhi(o[1]);
;                         v1[0] += bflo(o[2]); v1[1] += bfhi(o[2]); v1[2] += bflo(o[3]); v1[3] += bfhi(o[3]);
;                     }
;                     u32x4 w = {cvtpk(v0[0], v0[1]), cvtpk(v0[2], v0[3]), cvtpk(v1[0], v1[1]), cvtpk(v1[2], v1[3])};
;                     *(u32x4*)(op + bj * HALF) = w;
.LBB0_143:
	s_lshl_b32 s4, s24, 8
	s_ashr_i32 s6, s24, 2
	s_and_b32 s4, s4, 0x300
	v_or_b32_e32 v166, s4, v164
	s_lshl_b32 s4, s6, 10
	s_addk_i32 s4, 0x2000
	v_or_b32_e32 v167, s4, v166
	v_readlane_b32 s80, v255, 8
	s_cmp_gt_i32 s6, 0
	v_add_u32_e32 v0, v167, v147
	v_or_b32_e32 v142, v166, v148
	v_readlane_b32 s92, v255, 20
	v_readlane_b32 s93, v255, 21
	v_readlane_b32 s94, v255, 22
	v_readlane_b32 s95, v255, 23
	v_mov_b32_e32 v143, v1
	s_cselect_b64 s[4:5], -1, 0
	v_lshl_add_u64 v[144:145], v[0:1], 1, s[94:95]
	v_lshl_add_u64 v[142:143], v[142:143], 1, s[92:93]
	s_cmp_lt_i32 s6, 1
	v_readlane_b32 s81, v255, 9
	v_readlane_b32 s82, v255, 10
	v_readlane_b32 s83, v255, 11
	v_readlane_b32 s84, v255, 12
	v_readlane_b32 s85, v255, 13
	v_readlane_b32 s86, v255, 14
	v_readlane_b32 s87, v255, 15
	v_readlane_b32 s88, v255, 16
	v_readlane_b32 s89, v255, 17
	v_readlane_b32 s90, v255, 18
	v_readlane_b32 s91, v255, 19
	global_load_dwordx4 v[168:171], v[144:145], off
	global_load_dwordx4 v[218:221], v[144:145], off offset:256
	global_load_dwordx4 v[222:225], v[142:143], off
	global_load_dwordx4 v[226:229], v[142:143], off offset:256
	s_waitcnt vmcnt(3)
	v_lshlrev_b32_e32 v0, 16, v168
	v_mul_f32_e32 v0, 0xbfb8aa3b, v0
	v_exp_f32_e32 v0, v0
	s_nop 0
	v_add_f32_e32 v0, 1.0, v0
	v_rcp_f32_e32 v172, v0
	v_and_b32_e32 v0, 0xffff0000, v168
	v_mul_f32_e32 v0, 0xbfb8aa3b, v0
	v_exp_f32_e32 v0, v0
	s_nop 0
	v_add_f32_e32 v0, 1.0, v0
	v_rcp_f32_e32 v173, v0
	v_lshlrev_b32_e32 v0, 16, v169
	v_mul_f32_e32 v0, 0xbfb8aa3b, v0
	v_exp_f32_e32 v0, v0
	v_pk_mul_f32 v[126:127], v[126:127], v[172:173]
	v_add_f32_e32 v0, 1.0, v0
	v_rcp_f32_e32 v168, v0
	v_and_b32_e32 v0, 0xffff0000, v169
	v_mul_f32_e32 v0, 0xbfb8aa3b, v0
	v_exp_f32_e32 v0, v0
	s_nop 0
	v_add_f32_e32 v0, 1.0, v0
	v_rcp_f32_e32 v169, v0
	v_lshlrev_b32_e32 v0, 16, v170
	v_mul_f32_e32 v0, 0xbfb8aa3b, v0
	v_exp_f32_e32 v0, v0
	v_pk_mul_f32 v[128:129], v[128:129], v[168:169]
	v_add_f32_e32 v0, 1.0, v0
	v_rcp_f32_e32 v168, v0
	v_and_b32_e32 v0, 0xffff0000, v170
	v_mul_f32_e32 v0, 0xbfb8aa3b, v0
	v_exp_f32_e32 v0, v0
	s_nop 0
	v_add_f32_e32 v0, 1.0, v0
	v_rcp_f32_e32 v169, v0
	v_lshlrev_b32_e32 v0, 16, v171
	v_mul_f32_e32 v0, 0xbfb8aa3b, v0
	v_exp_f32_e32 v0, v0
	v_pk_mul_f32 v[122:123], v[122:123], v[168:169]
	v_add_f32_e32 v0, 1.0, v0
	v_rcp_f32_e32 v168, v0
	v_and_b32_e32 v0, 0xffff0000, v171
	v_mul_f32_e32 v0, 0xbfb8aa3b, v0
	v_exp_f32_e32 v0, v0
	s_nop 0
	v_add_f32_e32 v0, 1.0, v0
	v_rcp_f32_e32 v169, v0
	s_nop 0
	v_pk_mul_f32 v[124:125], v[124:125], v[168:169]
	s_cbranch_scc1 .LBB0_145
	s_waitcnt vmcnt(1)
	v_mov_b32_e32 v168, v222
	v_mov_b32_e32 v169, v223
	v_mov_b32_e32 v170, v224
	v_mov_b32_e32 v171, v225
	v_lshlrev_b32_e32 v172, 16, v168
	v_and_b32_e32 v173, 0xffff0000, v168
	v_lshlrev_b32_e32 v168, 16, v169
	v_and_b32_e32 v169, 0xffff0000, v169
	v_pk_add_f32 v[128:129], v[128:129], v[168:169]
	v_lshlrev_b32_e32 v168, 16, v170
	v_and_b32_e32 v169, 0xffff0000, v170
	v_pk_add_f32 v[122:123], v[122:123], v[168:169]
	v_lshlrev_b32_e32 v168, 16, v171
	v_and_b32_e32 v169, 0xffff0000, v171
	v_pk_add_f32 v[126:127], v[126:127], v[172:173]
	v_pk_add_f32 v[124:125], v[124:125], v[168:169]
.LBB0_145:
	v_cvt_pk_bf16_f32 v126, v126, v127
	v_cvt_pk_bf16_f32 v127, v128, v129
	v_cvt_pk_bf16_f32 v128, v122, v123
	s_nop 0
	v_cvt_pk_bf16_f32 v129, v124, v125
	global_store_dwordx4 v[142:143], v[126:129], off
	v_cndmask_b32_e64 v0, 0, 1, s[4:5]
	v_cmp_ne_u32_e64 s[36:37], 1, v0
	s_andn2_b64 vcc, exec, s[4:5]
	v_readlane_b32 s96, v255, 5
	s_brev_b32 s69, 18
	v_mov_b32_e32 v206, v208
	s_waitcnt vmcnt(2)
	v_mov_b32_e32 v122, v218
	v_mov_b32_e32 v123, v219
	v_mov_b32_e32 v124, v220
	v_mov_b32_e32 v125, v221
	v_lshlrev_b32_e32 v0, 16, v122
	v_and_b32_e32 v122, 0xffff0000, v122
	v_lshlrev_b32_e32 v126, 16, v123
	v_and_b32_e32 v123, 0xffff0000, v123
	v_lshlrev_b32_e32 v127, 16, v124
	v_and_b32_e32 v124, 0xffff0000, v124
	v_lshlrev_b32_e32 v128, 16, v125
	v_and_b32_e32 v125, 0xffff0000, v125
	v_mul_f32_e32 v0, 0xbfb8aa3b, v0
	v_mul_f32_e32 v122, 0xbfb8aa3b, v122
	v_mul_f32_e32 v126, 0xbfb8aa3b, v126
	v_mul_f32_e32 v123, 0xbfb8aa3b, v123
	v_mul_f32_e32 v127, 0xbfb8aa3b, v127
	v_mul_f32_e32 v124, 0xbfb8aa3b, v124
	v_mul_f32_e32 v128, 0xbfb8aa3b, v128
	v_mul_f32_e32 v125, 0xbfb8aa3b, v125
	v_exp_f32_e32 v0, v0
	v_exp_f32_e32 v122, v122
	v_exp_f32_e32 v126, v126
	v_exp_f32_e32 v123, v123
	v_exp_f32_e32 v127, v127
	v_exp_f32_e32 v124, v124
	v_exp_f32_e32 v128, v128
	v_exp_f32_e32 v125, v125
	v_add_f32_e32 v0, 1.0, v0
	v_add_f32_e32 v129, 1.0, v122
	v_add_f32_e32 v126, 1.0, v126
	v_add_f32_e32 v144, 1.0, v123
	v_add_f32_e32 v127, 1.0, v127
	v_add_f32_e32 v145, 1.0, v124
	v_add_f32_e32 v128, 1.0, v128
	v_add_f32_e32 v168, 1.0, v125
	v_rcp_f32_e32 v122, v0
	v_rcp_f32_e32 v123, v129
	v_rcp_f32_e32 v124, v126
	v_rcp_f32_e32 v125, v144
	v_rcp_f32_e32 v126, v127
	v_rcp_f32_e32 v127, v145
	v_rcp_f32_e32 v128, v128
	v_rcp_f32_e32 v129, v168
	v_pk_mul_f32 v[118:119], v[118:119], v[122:123]
	v_pk_mul_f32 v[120:121], v[120:121], v[124:125]
	v_pk_mul_f32 v[122:123], v[114:115], v[126:127]
	v_pk_mul_f32 v[114:115], v[116:117], v[128:129]
	s_cbranch_vccnz .LBB0_147
	s_waitcnt vmcnt(0)
	v_mov_b32_e32 v124, v226
	v_mov_b32_e32 v125, v227
	v_mov_b32_e32 v126, v228
	v_mov_b32_e32 v127, v229
	v_lshlrev_b32_e32 v116, 16, v124
	v_and_b32_e32 v117, 0xffff0000, v124
	v_pk_add_f32 v[118:119], v[118:119], v[116:117]
	v_lshlrev_b32_e32 v116, 16, v125
	v_and_b32_e32 v117, 0xffff0000, v125
	v_pk_add_f32 v[120:121], v[120:121], v[116:117]
	v_lshlrev_b32_e32 v116, 16, v126
	v_and_b32_e32 v117, 0xffff0000, v126
	v_pk_add_f32 v[122:123], v[122:123], v[116:117]
	v_lshlrev_b32_e32 v116, 16, v127
	v_and_b32_e32 v117, 0xffff0000, v127
	v_pk_add_f32 v[114:115], v[114:115], v[116:117]
; DI float bflo(unsigned w) { return __uint_as_float(w << 16); }
; DI float bfhi(unsigned w) { return __uint_as_float(w & 0xffff0000u); }
; DI unsigned cvtpk(float lo, float hi) { unsigned r; asm volatile("v_cvt_pk_bf16_f32 %0, %1, %2" : "=v"(r) : "v"(lo), "v"(hi)); return r; }
; DI float sigmoidf_(float x) { return __builtin_amdgcn_rcpf(1.f + __expf(-x)); }
;     __device__ __forceinline__ void operator()(const f32x4 (&acc)[2][2][4][2], const Unit& u, int wr, int wc, int fr, int fq) const {
;     ...
;                 const int row = u.pm * BM + ai * HALF + wr * 64 + m * 16 + fr;
;                 const int colb = pn * BM + wc * 32 + 8 * fq;
;                 const unsigned goff = (unsigned)(row * LDP + C_GT + br * 1024 + colb), ooff = (unsigned)(row * 1024 + colb);
;                 const bf16_t* gp = proj + goff;
;                 bf16_t* op = out + ooff;
;                 __builtin_amdgcn_sched_barrier(0);
; #pragma unroll
;                 for (int bj = 0; bj < 2; ++bj) {
;                     const u32x4 g = *(const u32x4*)(gp + bj * HALF);
;                     f32x4 v0 = acc[ai][bj][m][0], v1 = acc[ai][bj][m][1];
;                     v0[0] *= sigmoidf_(bflo(g[0])); v0[1] *= sigmoidf_(bfhi(g[0])); v0[2] *= sigmoidf_(bflo(g[1])); v0[3] *= sigmoidf_(bfhi(g[1]));
;                     v1[0] *= sigmoidf_(bflo(g[2])); v1[1] *= sigmoidf_(bfhi(g[2])); v1[2] *= sigmoidf_(bflo(g[3])); v1[3] *= sigmoidf_(bfhi(g[3]));
;                     if (br > 0) {
;                         const u32x4 o = *(const u32x4*)(op + bj * HALF);
;                         v0[0] += bflo(o[0]); v0[1] += bfhi(o[0]); v0[2] += bflo(o[1]); v0[3] += bfhi(o[1]);
;                         v1[0] += bflo(o[2]); v1[1] += bfhi(o[2]); v1[2] += bflo(o[3]); v1[3] += bfhi(o[3]);
;                     }
;                     u32x4 w = {cvtpk(v0[0], v0[1]), cvtpk(v0[2], v0[3]), cvtpk(v1[0], v1[1]), cvtpk(v1[2], v1[3])};
;                     *(u32x4*)(op + bj * HALF) = w;
.LBB0_147:
	v_readlane_b32 s80, v255, 8
	v_cvt_pk_bf16_f32 v116, v118, v119
	v_cvt_pk_bf16_f32 v117, v120, v121
	v_cvt_pk_bf16_f32 v118, v122, v123
	v_cvt_pk_bf16_f32 v119, v114, v115
	v_add_u32_e32 v0, v167, v149
	v_or_b32_e32 v114, v166, v150
	v_readlane_b32 s92, v255, 20
	v_readlane_b32 s93, v255, 21
	v_readlane_b32 s94, v255, 22
	v_readlane_b32 s95, v255, 23
	v_mov_b32_e32 v115, v1
	global_store_dwordx4 v[142:143], v[116:119], off offset:256
	v_lshl_add_u64 v[114:115], v[114:115], 1, s[92:93]
	v_readlane_b32 s81, v255, 9
	v_lshl_add_u64 v[116:117], v[0:1], 1, s[94:95]
	v_readlane_b32 s82, v255, 10
	v_readlane_b32 s83, v255, 11
	v_readlane_b32 s84, v255, 12
	v_readlane_b32 s85, v255, 13
	v_readlane_b32 s86, v255, 14
	v_readlane_b32 s87, v255, 15
	v_readlane_b32 s88, v255, 16
	v_readlane_b32 s89, v255, 17
	v_readlane_b32 s90, v255, 18
	v_readlane_b32 s91, v255, 19
	global_load_dwordx4 v[118:121], v[116:117], off
	global_load_dwordx4 v[218:221], v[116:117], off offset:256
	global_load_dwordx4 v[222:225], v[114:115], off
	global_load_dwordx4 v[226:229], v[114:115], off offset:256
	s_and_b64 vcc, exec, s[36:37]
	s_waitcnt vmcnt(3)
	v_lshlrev_b32_e32 v0, 16, v118
	v_mul_f32_e32 v0, 0xbfb8aa3b, v0
	v_exp_f32_e32 v0, v0
	s_nop 0
	v_add_f32_e32 v0, 1.0, v0
	v_rcp_f32_e32 v122, v0
	v_and_b32_e32 v0, 0xffff0000, v118
	v_mul_f32_e32 v0, 0xbfb8aa3b, v0
	v_exp_f32_e32 v0, v0
	s_nop 0
	v_add_f32_e32 v0, 1.0, v0
	v_rcp_f32_e32 v123, v0
	v_lshlrev_b32_e32 v0, 16, v119
	v_mul_f32_e32 v0, 0xbfb8aa3b, v0
	v_exp_f32_e32 v0, v0
	v_pk_mul_f32 v[110:111], v[110:111], v[122:123]
	v_add_f32_e32 v0, 1.0, v0
	v_rcp_f32_e32 v118, v0
	v_and_b32_e32 v0, 0xffff0000, v119
	v_mul_f32_e32 v0, 0xbfb8aa3b, v0
	v_exp_f32_e32 v0, v0
	s_nop 0
	v_add_f32_e32 v0, 1.0, v0
	v_rcp_f32_e32 v119, v0
	v_lshlrev_b32_e32 v0, 16, v120
	v_mul_f32_e32 v0, 0xbfb8aa3b, v0
	v_exp_f32_e32 v0, v0
	v_pk_mul_f32 v[112:113], v[112:113], v[118:119]
	v_add_f32_e32 v0, 1.0, v0
	v_rcp_f32_e32 v118, v0
	v_and_b32_e32 v0, 0xffff0000, v120
	v_mul_f32_e32 v0, 0xbfb8aa3b, v0
	v_exp_f32_e32 v0, v0
	s_nop 0
	v_add_f32_e32 v0, 1.0, v0
	v_rcp_f32_e32 v119, v0
	v_lshlrev_b32_e32 v0, 16, v121
	v_mul_f32_e32 v0, 0xbfb8aa3b, v0
	v_exp_f32_e32 v0, v0
	v_pk_mul_f32 v[106:107], v[106:107], v[118:119]
	v_add_f32_e32 v0, 1.0, v0
	v_rcp_f32_e32 v118, v0
	v_and_b32_e32 v0, 0xffff0000, v121
	v_mul_f32_e32 v0, 0xbfb8aa3b, v0
	v_exp_f32_e32 v0, v0
	s_nop 0
	v_add_f32_e32 v0, 1.0, v0
	v_rcp_f32_e32 v119, v0
	s_nop 0
	v_pk_mul_f32 v[108:109], v[108:109], v[118:119]
	s_cbranch_vccnz .LBB0_149
	s_waitcnt vmcnt(1)
	v_mov_b32_e32 v118, v222
	v_mov_b32_e32 v119, v223
	v_mov_b32_e32 v120, v224
	v_mov_b32_e32 v121, v225
	v_lshlrev_b32_e32 v122, 16, v118
	v_and_b32_e32 v123, 0xffff0000, v118
	v_lshlrev_b32_e32 v118, 16, v119
	v_and_b32_e32 v119, 0xffff0000, v119
	v_pk_add_f32 v[112:113], v[112:113], v[118:119]
	v_lshlrev_b32_e32 v118, 16, v120
	v_and_b32_e32 v119, 0xffff0000, v120
	v_pk_add_f32 v[106:107], v[106:107], v[118:119]
	v_lshlrev_b32_e32 v118, 16, v121
	v_and_b32_e32 v119, 0xffff0000, v121
	v_pk_add_f32 v[110:111], v[110:111], v[122:123]
	v_pk_add_f32 v[108:109], v[108:109], v[118:119]
.LBB0_149:
	v_cvt_pk_bf16_f32 v110, v110, v111
	v_cvt_pk_bf16_f32 v111, v112, v113
	v_cvt_pk_bf16_f32 v112, v106, v107
	s_nop 0
	v_cvt_pk_bf16_f32 v113, v108, v109
	global_store_dwordx4 v[114:115], v[110:113], off
	s_and_b64 vcc, exec, s[36:37]
	s_waitcnt vmcnt(2)
	v_mov_b32_e32 v106, v218
	v_mov_b32_e32 v107, v219
	v_mov_b32_e32 v108, v220
	v_mov_b32_e32 v109, v221
	v_lshlrev_b32_e32 v0, 16, v106
	v_and_b32_e32 v106, 0xffff0000, v106
	v_lshlrev_b32_e32 v110, 16, v107
	v_and_b32_e32 v107, 0xffff0000, v107
	v_lshlrev_b32_e32 v111, 16, v108
	v_and_b32_e32 v108, 0xffff0000, v108
	v_lshlrev_b32_e32 v112, 16, v109
	v_and_b32_e32 v109, 0xffff0000, v109
	v_mul_f32_e32 v0, 0xbfb8aa3b, v0
	v_mul_f32_e32 v106, 0xbfb8aa3b, v106
	v_mul_f32_e32 v110, 0xbfb8aa3b, v110
	v_mul_f32_e32 v107, 0xbfb8aa3b, v107
	v_mul_f32_e32 v111, 0xbfb8aa3b, v111
	v_mul_f32_e32 v108, 0xbfb8aa3b, v108
	v_mul_f32_e32 v112, 0xbfb8aa3b, v112
	v_mul_f32_e32 v109, 0xbfb8aa3b, v109
	v_exp_f32_e32 v0, v0
	v_exp_f32_e32 v106, v106
	v_exp_f32_e32 v110, v110
	v_exp_f32_e32 v107, v107
	v_exp_f32_e32 v111, v111
	v_exp_f32_e32 v108, v108
	v_exp_f32_e32 v112, v112
	v_exp_f32_e32 v109, v109
	v_add_f32_e32 v0, 1.0, v0
	v_add_f32_e32 v113, 1.0, v106
	v_add_f32_e32 v110, 1.0, v110
	v_add_f32_e32 v116, 1.0, v107
	v_add_f32_e32 v111, 1.0, v111
	v_add_f32_e32 v117, 1.0, v108
	v_add_f32_e32 v112, 1.0, v112
	v_add_f32_e32 v118, 1.0, v109
	v_rcp_f32_e32 v106, v0
	v_rcp_f32_e32 v107, v113
	v_rcp_f32_e32 v108, v110
	v_rcp_f32_e32 v109, v116
	v_rcp_f32_e32 v110, v111
	v_rcp_f32_e32 v111, v117
	v_rcp_f32_e32 v112, v112
	v_rcp_f32_e32 v113, v118
	v_pk_mul_f32 v[102:103], v[102:103], v[106:107]
	v_pk_mul_f32 v[104:105], v[104:105], v[108:109]
	v_pk_mul_f32 v[106:107], v[98:99], v[110:111]
	v_pk_mul_f32 v[98:99], v[100:101], v[112:113]
	s_cbranch_vccnz .LBB0_151
	s_waitcnt vmcnt(0)
	v_mov_b32_e32 v108, v226
	v_mov_b32_e32 v109, v227
	v_mov_b32_e32 v110, v228
	v_mov_b32_e32 v111, v229
	v_lshlrev_b32_e32 v100, 16, v108
	v_and_b32_e32 v101, 0xffff0000, v108
	v_pk_add_f32 v[102:103], v[102:103], v[100:101]
	v_lshlrev_b32_e32 v100, 16, v109
	v_and_b32_e32 v101, 0xffff0000, v109
	v_pk_add_f32 v[104:105], v[104:105], v[100:101]
	v_lshlrev_b32_e32 v100, 16, v110
	v_and_b32_e32 v101, 0xffff0000, v110
	v_pk_add_f32 v[106:107], v[106:107], v[100:101]
	v_lshlrev_b32_e32 v100, 16, v111
	v_and_b32_e32 v101, 0xffff0000, v111
	v_pk_add_f32 v[98:99], v[98:99], v[100:101]
; DI float bflo(unsigned w) { return __uint_as_float(w << 16); }
; DI float bfhi(unsigned w) { return __uint_as_float(w & 0xffff0000u); }
; DI unsigned cvtpk(float lo, float hi) { unsigned r; asm volatile("v_cvt_pk_bf16_f32 %0, %1, %2" : "=v"(r) : "v"(lo), "v"(hi)); return r; }
; DI float sigmoidf_(float x) { return __builtin_amdgcn_rcpf(1.f + __expf(-x)); }
;     __device__ __forceinline__ void operator()(const f32x4 (&acc)[2][2][4][2], const Unit& u, int wr, int wc, int fr, int fq) const {
;     ...
;                 const int row = u.pm * BM + ai * HALF + wr * 64 + m * 16 + fr;
;                 const int colb = pn * BM + wc * 32 + 8 * fq;
;                 const unsigned goff = (unsigned)(row * LDP + C_GT + br * 1024 + colb), ooff = (unsigned)(row * 1024 + colb);
;                 const bf16_t* gp = proj + goff;
;                 bf16_t* op = out + ooff;
;                 __builtin_amdgcn_sched_barrier(0);
; #pragma unroll
;                 for (int bj = 0; bj < 2; ++bj) {
;                     const u32x4 g = *(const u32x4*)(gp + bj * HALF);
;                     f32x4 v0 = acc[ai][bj][m][0], v1 = acc[ai][bj][m][1];
;                     v0[0] *= sigmoidf_(bflo(g[0])); v0[1] *= sigmoidf_(bfhi(g[0])); v0[2] *= sigmoidf_(bflo(g[1])); v0[3] *= sigmoidf_(bfhi(g[1]));
;                     v1[0] *= sigmoidf_(bflo(g[2])); v1[1] *= sigmoidf_(bfhi(g[2])); v1[2] *= sigmoidf_(bflo(g[3])); v1[3] *= sigmoidf_(bfhi(g[3]));
;                     if (br > 0) {
;                         const u32x4 o = *(const u32x4*)(op + bj * HALF);
;                         v0[0] += bflo(o[0]); v0[1] += bfhi(o[0]); v0[2] += bflo(o[1]); v0[3] += bfhi(o[1]);
;                         v1[0] += bflo(o[2]); v1[1] += bfhi(o[2]); v1[2] += bflo(o[3]); v1[3] += bfhi(o[3]);
;                     }
;                     u32x4 w = {cvtpk(v0[0], v0[1]), cvtpk(v0[2], v0[3]), cvtpk(v1[0], v1[1]), cvtpk(v1[2], v1[3])};
;                     *(u32x4*)(op + bj * HALF) = w;
.LBB0_151:
	v_readlane_b32 s80, v255, 8
	v_cvt_pk_bf16_f32 v100, v102, v103
	v_cvt_pk_bf16_f32 v101, v104, v105
	v_cvt_pk_bf16_f32 v102, v106, v107
	v_cvt_pk_bf16_f32 v103, v98, v99
	v_add_u32_e32 v0, v167, v151
	v_or_b32_e32 v98, v166, v152
	v_readlane_b32 s92, v255, 20
	v_readlane_b32 s93, v255, 21
	v_readlane_b32 s94, v255, 22
	v_readlane_b32 s95, v255, 23
	v_mov_b32_e32 v99, v1
	global_store_dwordx4 v[114:115], v[100:103], off offset:256
	v_lshl_add_u64 v[98:99], v[98:99], 1, s[92:93]
	v_readlane_b32 s81, v255, 9
	v_lshl_add_u64 v[100:101], v[0:1], 1, s[94:95]
	v_readlane_b32 s82, v255, 10
	v_readlane_b32 s83, v255, 11
	v_readlane_b32 s84, v255, 12
	v_readlane_b32 s85, v255, 13
	v_readlane_b32 s86, v255, 14
	v_readlane_b32 s87, v255, 15
	v_readlane_b32 s88, v255, 16
	v_readlane_b32 s89, v255, 17
	v_readlane_b32 s90, v255, 18
	v_readlane_b32 s91, v255, 19
	global_load_dwordx4 v[102:105], v[100:101], off
	global_load_dwordx4 v[218:221], v[100:101], off offset:256
	global_load_dwordx4 v[222:225], v[98:99], off
	global_load_dwordx4 v[226:229], v[98:99], off offset:256
	s_and_b64 vcc, exec, s[36:37]
	s_waitcnt vmcnt(3)
	v_lshlrev_b32_e32 v0, 16, v102
	v_mul_f32_e32 v0, 0xbfb8aa3b, v0
	v_exp_f32_e32 v0, v0
	s_nop 0
	v_add_f32_e32 v0, 1.0, v0
	v_rcp_f32_e32 v106, v0
	v_and_b32_e32 v0, 0xffff0000, v102
	v_mul_f32_e32 v0, 0xbfb8aa3b, v0
	v_exp_f32_e32 v0, v0
	s_nop 0
	v_add_f32_e32 v0, 1.0, v0
	v_rcp_f32_e32 v107, v0
	v_lshlrev_b32_e32 v0, 16, v103
	v_mul_f32_e32 v0, 0xbfb8aa3b, v0
	v_exp_f32_e32 v0, v0
	v_pk_mul_f32 v[94:95], v[94:95], v[106:107]
	v_add_f32_e32 v0, 1.0, v0
	v_rcp_f32_e32 v102, v0
	v_and_b32_e32 v0, 0xffff0000, v103
	v_mul_f32_e32 v0, 0xbfb8aa3b, v0
	v_exp_f32_e32 v0, v0
	s_nop 0
	v_add_f32_e32 v0, 1.0, v0
	v_rcp_f32_e32 v103, v0
	v_lshlrev_b32_e32 v0, 16, v104
	v_mul_f32_e32 v0, 0xbfb8aa3b, v0
	v_exp_f32_e32 v0, v0
	v_pk_mul_f32 v[96:97], v[96:97], v[102:103]
	v_add_f32_e32 v0, 1.0, v0
	v_rcp_f32_e32 v102, v0
	v_and_b32_e32 v0, 0xffff0000, v104
	v_mul_f32_e32 v0, 0xbfb8aa3b, v0
	v_exp_f32_e32 v0, v0
	s_nop 0
	v_add_f32_e32 v0, 1.0, v0
	v_rcp_f32_e32 v103, v0
	v_lshlrev_b32_e32 v0, 16, v105
	v_mul_f32_e32 v0, 0xbfb8aa3b, v0
	v_exp_f32_e32 v0, v0
	v_pk_mul_f32 v[90:91], v[90:91], v[102:103]
	v_add_f32_e32 v0, 1.0, v0
	v_rcp_f32_e32 v102, v0
	v_and_b32_e32 v0, 0xffff0000, v105
	v_mul_f32_e32 v0, 0xbfb8aa3b, v0
	v_exp_f32_e32 v0, v0
	s_nop 0
	v_add_f32_e32 v0, 1.0, v0
	v_rcp_f32_e32 v103, v0
	s_nop 0
	v_pk_mul_f32 v[92:93], v[92:93], v[102:103]
	s_cbranch_vccnz .LBB0_153
	s_waitcnt vmcnt(1)
	v_mov_b32_e32 v102, v222
	v_mov_b32_e32 v103, v223
	v_mov_b32_e32 v104, v224
	v_mov_b32_e32 v105, v225
	v_lshlrev_b32_e32 v106, 16, v102
	v_and_b32_e32 v107, 0xffff0000, v102
	v_lshlrev_b32_e32 v102, 16, v103
	v_and_b32_e32 v103, 0xffff0000, v103
	v_pk_add_f32 v[96:97], v[96:97], v[102:103]
	v_lshlrev_b32_e32 v102, 16, v104
	v_and_b32_e32 v103, 0xffff0000, v104
	v_pk_add_f32 v[90:91], v[90:91], v[102:103]
	v_lshlrev_b32_e32 v102, 16, v105
	v_and_b32_e32 v103, 0xffff0000, v105
	v_pk_add_f32 v[94:95], v[94:95], v[106:107]
	v_pk_add_f32 v[92:93], v[92:93], v[102:103]
.LBB0_153:
	v_cvt_pk_bf16_f32 v94, v94, v95
	v_cvt_pk_bf16_f32 v95, v96, v97
	v_cvt_pk_bf16_f32 v96, v90, v91
	s_nop 0
	v_cvt_pk_bf16_f32 v97, v92, v93
	global_store_dwordx4 v[98:99], v[94:97], off
	s_and_b64 vcc, exec, s[36:37]
	s_waitcnt vmcnt(2)
	v_mov_b32_e32 v90, v218
	v_mov_b32_e32 v91, v219
	v_mov_b32_e32 v92, v220
	v_mov_b32_e32 v93, v221
	v_lshlrev_b32_e32 v0, 16, v90
	v_and_b32_e32 v90, 0xffff0000, v90
	v_lshlrev_b32_e32 v94, 16, v91
	v_and_b32_e32 v91, 0xffff0000, v91
	v_lshlrev_b32_e32 v95, 16, v92
	v_and_b32_e32 v92, 0xffff0000, v92
	v_lshlrev_b32_e32 v96, 16, v93
	v_and_b32_e32 v93, 0xffff0000, v93
	v_mul_f32_e32 v0, 0xbfb8aa3b, v0
	v_mul_f32_e32 v90, 0xbfb8aa3b, v90
	v_mul_f32_e32 v94, 0xbfb8aa3b, v94
	v_mul_f32_e32 v91, 0xbfb8aa3b, v91
	v_mul_f32_e32 v95, 0xbfb8aa3b, v95
	v_mul_f32_e32 v92, 0xbfb8aa3b, v92
	v_mul_f32_e32 v96, 0xbfb8aa3b, v96
	v_mul_f32_e32 v93, 0xbfb8aa3b, v93
	v_exp_f32_e32 v0, v0
	v_exp_f32_e32 v90, v90
	v_exp_f32_e32 v94, v94
	v_exp_f32_e32 v91, v91
	v_exp_f32_e32 v95, v95
	v_exp_f32_e32 v92, v92
	v_exp_f32_e32 v96, v96
	v_exp_f32_e32 v93, v93
	v_add_f32_e32 v0, 1.0, v0
	v_add_f32_e32 v97, 1.0, v90
	v_add_f32_e32 v94, 1.0, v94
	v_add_f32_e32 v100, 1.0, v91
	v_add_f32_e32 v95, 1.0, v95
	v_add_f32_e32 v101, 1.0, v92
	v_add_f32_e32 v96, 1.0, v96
	v_add_f32_e32 v102, 1.0, v93
	v_rcp_f32_e32 v90, v0
	v_rcp_f32_e32 v91, v97
	v_rcp_f32_e32 v92, v94
	v_rcp_f32_e32 v93, v100
	v_rcp_f32_e32 v94, v95
	v_rcp_f32_e32 v95, v101
	v_rcp_f32_e32 v96, v96
	v_rcp_f32_e32 v97, v102
	v_pk_mul_f32 v[86:87], v[86:87], v[90:91]
	v_pk_mul_f32 v[88:89], v[88:89], v[92:93]
	v_pk_mul_f32 v[90:91], v[82:83], v[94:95]
	v_pk_mul_f32 v[82:83], v[84:85], v[96:97]
	s_cbranch_vccnz .LBB0_155
	s_waitcnt vmcnt(0)
	v_mov_b32_e32 v92, v226
	v_mov_b32_e32 v93, v227
	v_mov_b32_e32 v94, v228
	v_mov_b32_e32 v95, v229
	v_lshlrev_b32_e32 v84, 16, v92
	v_and_b32_e32 v85, 0xffff0000, v92
	v_pk_add_f32 v[86:87], v[86:87], v[84:85]
	v_lshlrev_b32_e32 v84, 16, v93
	v_and_b32_e32 v85, 0xffff0000, v93
	v_pk_add_f32 v[88:89], v[88:89], v[84:85]
	v_lshlrev_b32_e32 v84, 16, v94
	v_and_b32_e32 v85, 0xffff0000, v94
	v_pk_add_f32 v[90:91], v[90:91], v[84:85]
	v_lshlrev_b32_e32 v84, 16, v95
	v_and_b32_e32 v85, 0xffff0000, v95
	v_pk_add_f32 v[82:83], v[82:83], v[84:85]
; DI float bflo(unsigned w) { return __uint_as_float(w << 16); }
; DI float bfhi(unsigned w) { return __uint_as_float(w & 0xffff0000u); }
; DI unsigned cvtpk(float lo, float hi) { unsigned r; asm volatile("v_cvt_pk_bf16_f32 %0, %1, %2" : "=v"(r) : "v"(lo), "v"(hi)); return r; }
; DI float sigmoidf_(float x) { return __builtin_amdgcn_rcpf(1.f + __expf(-x)); }
;     __device__ __forceinline__ void operator()(const f32x4 (&acc)[2][2][4][2], const Unit& u, int wr, int wc, int fr, int fq) const {
;     ...
;                 const int row = u.pm * BM + ai * HALF + wr * 64 + m * 16 + fr;
;                 const int colb = pn * BM + wc * 32 + 8 * fq;
;                 const unsigned goff = (unsigned)(row * LDP + C_GT + br * 1024 + colb), ooff = (unsigned)(row * 1024 + colb);
;                 const bf16_t* gp = proj + goff;
;                 bf16_t* op = out + ooff;
;                 __builtin_amdgcn_sched_barrier(0);
; #pragma unroll
;                 for (int bj = 0; bj < 2; ++bj) {
;                     const u32x4 g = *(const u32x4*)(gp + bj * HALF);
;                     f32x4 v0 = acc[ai][bj][m][0], v1 = acc[ai][bj][m][1];
;                     v0[0] *= sigmoidf_(bflo(g[0])); v0[1] *= sigmoidf_(bfhi(g[0])); v0[2] *= sigmoidf_(bflo(g[1])); v0[3] *= sigmoidf_(bfhi(g[1]));
;                     v1[0] *= sigmoidf_(bflo(g[2])); v1[1] *= sigmoidf_(bfhi(g[2])); v1[2] *= sigmoidf_(bflo(g[3])); v1[3] *= sigmoidf_(bfhi(g[3]));
;                     if (br > 0) {
;                         const u32x4 o = *(const u32x4*)(op + bj * HALF);
;                         v0[0] += bflo(o[0]); v0[1] += bfhi(o[0]); v0[2] += bflo(o[1]); v0[3] += bfhi(o[1]);
;                         v1[0] += bflo(o[2]); v1[1] += bfhi(o[2]); v1[2] += bflo(o[3]); v1[3] += bfhi(o[3]);
;                     }
;                     u32x4 w = {cvtpk(v0[0], v0[1]), cvtpk(v0[2], v0[3]), cvtpk(v1[0], v1[1]), cvtpk(v1[2], v1[3])};
;                     *(u32x4*)(op + bj * HALF) = w;
.LBB0_155:
	v_readlane_b32 s80, v255, 8
	v_cvt_pk_bf16_f32 v84, v86, v87
	v_cvt_pk_bf16_f32 v85, v88, v89
	v_cvt_pk_bf16_f32 v86, v90, v91
	v_cvt_pk_bf16_f32 v87, v82, v83
	v_add_u32_e32 v0, v167, v153
	v_or_b32_e32 v82, v166, v154
	v_readlane_b32 s92, v255, 20
	v_readlane_b32 s93, v255, 21
	v_readlane_b32 s94, v255, 22
	v_readlane_b32 s95, v255, 23
	v_mov_b32_e32 v83, v1
	global_store_dwordx4 v[98:99], v[84:87], off offset:256
	v_lshl_add_u64 v[82:83], v[82:83], 1, s[92:93]
	v_readlane_b32 s81, v255, 9
	v_lshl_add_u64 v[84:85], v[0:1], 1, s[94:95]
	v_readlane_b32 s82, v255, 10
	v_readlane_b32 s83, v255, 11
	v_readlane_b32 s84, v255, 12
	v_readlane_b32 s85, v255, 13
	v_readlane_b32 s86, v255, 14
	v_readlane_b32 s87, v255, 15
	v_readlane_b32 s88, v255, 16
	v_readlane_b32 s89, v255, 17
	v_readlane_b32 s90, v255, 18
	v_readlane_b32 s91, v255, 19
	global_load_dwordx4 v[86:89], v[84:85], off
	global_load_dwordx4 v[218:221], v[84:85], off offset:256
	global_load_dwordx4 v[222:225], v[82:83], off
	global_load_dwordx4 v[226:229], v[82:83], off offset:256
	s_and_b64 vcc, exec, s[36:37]
	s_waitcnt vmcnt(3)
	v_lshlrev_b32_e32 v0, 16, v86
	v_mul_f32_e32 v0, 0xbfb8aa3b, v0
	v_exp_f32_e32 v0, v0
	s_nop 0
	v_add_f32_e32 v0, 1.0, v0
	v_rcp_f32_e32 v90, v0
	v_and_b32_e32 v0, 0xffff0000, v86
	v_mul_f32_e32 v0, 0xbfb8aa3b, v0
	v_exp_f32_e32 v0, v0
	s_nop 0
	v_add_f32_e32 v0, 1.0, v0
	v_rcp_f32_e32 v91, v0
	v_lshlrev_b32_e32 v0, 16, v87
	v_mul_f32_e32 v0, 0xbfb8aa3b, v0
	v_exp_f32_e32 v0, v0
	v_pk_mul_f32 v[78:79], v[78:79], v[90:91]
	v_add_f32_e32 v0, 1.0, v0
	v_rcp_f32_e32 v86, v0
	v_and_b32_e32 v0, 0xffff0000, v87
	v_mul_f32_e32 v0, 0xbfb8aa3b, v0
	v_exp_f32_e32 v0, v0
	s_nop 0
	v_add_f32_e32 v0, 1.0, v0
	v_rcp_f32_e32 v87, v0
	v_lshlrev_b32_e32 v0, 16, v88
	v_mul_f32_e32 v0, 0xbfb8aa3b, v0
	v_exp_f32_e32 v0, v0
	v_pk_mul_f32 v[80:81], v[80:81], v[86:87]
	v_add_f32_e32 v0, 1.0, v0
	v_rcp_f32_e32 v86, v0
	v_and_b32_e32 v0, 0xffff0000, v88
	v_mul_f32_e32 v0, 0xbfb8aa3b, v0
	v_exp_f32_e32 v0, v0
	s_nop 0
	v_add_f32_e32 v0, 1.0, v0
	v_rcp_f32_e32 v87, v0
	v_lshlrev_b32_e32 v0, 16, v89
	v_mul_f32_e32 v0, 0xbfb8aa3b, v0
	v_exp_f32_e32 v0, v0
	v_pk_mul_f32 v[74:75], v[74:75], v[86:87]
	v_add_f32_e32 v0, 1.0, v0
	v_rcp_f32_e32 v86, v0
	v_and_b32_e32 v0, 0xffff0000, v89
	v_mul_f32_e32 v0, 0xbfb8aa3b, v0
	v_exp_f32_e32 v0, v0
	s_nop 0
	v_add_f32_e32 v0, 1.0, v0
	v_rcp_f32_e32 v87, v0
	s_nop 0
	v_pk_mul_f32 v[76:77], v[76:77], v[86:87]
	s_cbranch_vccnz .LBB0_157
	s_waitcnt vmcnt(1)
	v_mov_b32_e32 v86, v222
	v_mov_b32_e32 v87, v223
	v_mov_b32_e32 v88, v224
	v_mov_b32_e32 v89, v225
	v_lshlrev_b32_e32 v90, 16, v86
	v_and_b32_e32 v91, 0xffff0000, v86
	v_lshlrev_b32_e32 v86, 16, v87
	v_and_b32_e32 v87, 0xffff0000, v87
	v_pk_add_f32 v[80:81], v[80:81], v[86:87]
	v_lshlrev_b32_e32 v86, 16, v88
	v_and_b32_e32 v87, 0xffff0000, v88
	v_pk_add_f32 v[74:75], v[74:75], v[86:87]
	v_lshlrev_b32_e32 v86, 16, v89
	v_and_b32_e32 v87, 0xffff0000, v89
	v_pk_add_f32 v[78:79], v[78:79], v[90:91]
	v_pk_add_f32 v[76:77], v[76:77], v[86:87]
.LBB0_157:
	v_cvt_pk_bf16_f32 v78, v78, v79
	v_cvt_pk_bf16_f32 v79, v80, v81
	v_cvt_pk_bf16_f32 v80, v74, v75
	s_nop 0
	v_cvt_pk_bf16_f32 v81, v76, v77
	global_store_dwordx4 v[82:83], v[78:81], off
	s_and_b64 vcc, exec, s[36:37]
	s_waitcnt vmcnt(2)
	v_mov_b32_e32 v74, v218
	v_mov_b32_e32 v75, v219
	v_mov_b32_e32 v76, v220
	v_mov_b32_e32 v77, v221
	v_lshlrev_b32_e32 v0, 16, v74
	v_and_b32_e32 v74, 0xffff0000, v74
	v_lshlrev_b32_e32 v78, 16, v75
	v_and_b32_e32 v75, 0xffff0000, v75
	v_lshlrev_b32_e32 v79, 16, v76
	v_and_b32_e32 v76, 0xffff0000, v76
	v_lshlrev_b32_e32 v80, 16, v77
	v_and_b32_e32 v77, 0xffff0000, v77
	v_mul_f32_e32 v0, 0xbfb8aa3b, v0
	v_mul_f32_e32 v74, 0xbfb8aa3b, v74
	v_mul_f32_e32 v78, 0xbfb8aa3b, v78
	v_mul_f32_e32 v75, 0xbfb8aa3b, v75
	v_mul_f32_e32 v79, 0xbfb8aa3b, v79
	v_mul_f32_e32 v76, 0xbfb8aa3b, v76
	v_mul_f32_e32 v80, 0xbfb8aa3b, v80
	v_mul_f32_e32 v77, 0xbfb8aa3b, v77
	v_exp_f32_e32 v0, v0
	v_exp_f32_e32 v74, v74
	v_exp_f32_e32 v78, v78
	v_exp_f32_e32 v75, v75
	v_exp_f32_e32 v79, v79
	v_exp_f32_e32 v76, v76
	v_exp_f32_e32 v80, v80
	v_exp_f32_e32 v77, v77
	v_add_f32_e32 v0, 1.0, v0
	v_add_f32_e32 v81, 1.0, v74
	v_add_f32_e32 v78, 1.0, v78
	v_add_f32_e32 v84, 1.0, v75
	v_add_f32_e32 v79, 1.0, v79
	v_add_f32_e32 v85, 1.0, v76
	v_add_f32_e32 v80, 1.0, v80
	v_add_f32_e32 v86, 1.0, v77
	v_rcp_f32_e32 v74, v0
	v_rcp_f32_e32 v75, v81
	v_rcp_f32_e32 v76, v78
	v_rcp_f32_e32 v77, v84
	v_rcp_f32_e32 v78, v79
	v_rcp_f32_e32 v79, v85
	v_rcp_f32_e32 v80, v80
	v_rcp_f32_e32 v81, v86
	v_pk_mul_f32 v[70:71], v[70:71], v[74:75]
	v_pk_mul_f32 v[72:73], v[72:73], v[76:77]
	v_pk_mul_f32 v[74:75], v[66:67], v[78:79]
	v_pk_mul_f32 v[66:67], v[68:69], v[80:81]
	s_cbranch_vccnz .LBB0_159
	s_waitcnt vmcnt(0)
	v_mov_b32_e32 v76, v226
	v_mov_b32_e32 v77, v227
	v_mov_b32_e32 v78, v228
	v_mov_b32_e32 v79, v229
	v_lshlrev_b32_e32 v68, 16, v76
	v_and_b32_e32 v69, 0xffff0000, v76
	v_pk_add_f32 v[70:71], v[70:71], v[68:69]
	v_lshlrev_b32_e32 v68, 16, v77
	v_and_b32_e32 v69, 0xffff0000, v77
	v_pk_add_f32 v[72:73], v[72:73], v[68:69]
	v_lshlrev_b32_e32 v68, 16, v78
	v_and_b32_e32 v69, 0xffff0000, v78
	v_pk_add_f32 v[74:75], v[74:75], v[68:69]
	v_lshlrev_b32_e32 v68, 16, v79
	v_and_b32_e32 v69, 0xffff0000, v79
	v_pk_add_f32 v[66:67], v[66:67], v[68:69]
; DI float bflo(unsigned w) { return __uint_as_float(w << 16); }
; DI float bfhi(unsigned w) { return __uint_as_float(w & 0xffff0000u); }
; DI unsigned cvtpk(float lo, float hi) { unsigned r; asm volatile("v_cvt_pk_bf16_f32 %0, %1, %2" : "=v"(r) : "v"(lo), "v"(hi)); return r; }
; DI float sigmoidf_(float x) { return __builtin_amdgcn_rcpf(1.f + __expf(-x)); }
;     __device__ __forceinline__ void operator()(const f32x4 (&acc)[2][2][4][2], const Unit& u, int wr, int wc, int fr, int fq) const {
;     ...
;                 const int row = u.pm * BM + ai * HALF + wr * 64 + m * 16 + fr;
;                 const int colb = pn * BM + wc * 32 + 8 * fq;
;                 const unsigned goff = (unsigned)(row * LDP + C_GT + br * 1024 + colb), ooff = (unsigned)(row * 1024 + colb);
;                 const bf16_t* gp = proj + goff;
;                 bf16_t* op = out + ooff;
;                 __builtin_amdgcn_sched_barrier(0);
; #pragma unroll
;                 for (int bj = 0; bj < 2; ++bj) {
;                     const u32x4 g = *(const u32x4*)(gp + bj * HALF);
;                     f32x4 v0 = acc[ai][bj][m][0], v1 = acc[ai][bj][m][1];
;                     v0[0] *= sigmoidf_(bflo(g[0])); v0[1] *= sigmoidf_(bfhi(g[0])); v0[2] *= sigmoidf_(bflo(g[1])); v0[3] *= sigmoidf_(bfhi(g[1]));
;                     v1[0] *= sigmoidf_(bflo(g[2])); v1[1] *= sigmoidf_(bfhi(g[2])); v1[2] *= sigmoidf_(bflo(g[3])); v1[3] *= sigmoidf_(bfhi(g[3]));
;                     if (br > 0) {
;                         const u32x4 o = *(const u32x4*)(op + bj * HALF);
;                         v0[0] += bflo(o[0]); v0[1] += bfhi(o[0]); v0[2] += bflo(o[1]); v0[3] += bfhi(o[1]);
;                         v1[0] += bflo(o[2]); v1[1] += bfhi(o[2]); v1[2] += bflo(o[3]); v1[3] += bfhi(o[3]);
;                     }
;                     u32x4 w = {cvtpk(v0[0], v0[1]), cvtpk(v0[2], v0[3]), cvtpk(v1[0], v1[1]), cvtpk(v1[2], v1[3])};
;                     *(u32x4*)(op + bj * HALF) = w;
.LBB0_159:
	v_readlane_b32 s80, v255, 8
	v_cvt_pk_bf16_f32 v68, v70, v71
	v_cvt_pk_bf16_f32 v69, v72, v73
	v_cvt_pk_bf16_f32 v70, v74, v75
	v_cvt_pk_bf16_f32 v71, v66, v67
	v_add_u32_e32 v0, v167, v155
	v_or_b32_e32 v66, v166, v157
	v_readlane_b32 s92, v255, 20
	v_readlane_b32 s93, v255, 21
	v_readlane_b32 s94, v255, 22
	v_readlane_b32 s95, v255, 23
	v_mov_b32_e32 v67, v1
	global_store_dwordx4 v[82:83], v[68:71], off offset:256
	v_lshl_add_u64 v[66:67], v[66:67], 1, s[92:93]
	v_readlane_b32 s81, v255, 9
	v_lshl_add_u64 v[68:69], v[0:1], 1, s[94:95]
	v_readlane_b32 s82, v255, 10
	v_readlane_b32 s83, v255, 11
	v_readlane_b32 s84, v255, 12
	v_readlane_b32 s85, v255, 13
	v_readlane_b32 s86, v255, 14
	v_readlane_b32 s87, v255, 15
	v_readlane_b32 s88, v255, 16
	v_readlane_b32 s89, v255, 17
	v_readlane_b32 s90, v255, 18
	v_readlane_b32 s91, v255, 19
	global_load_dwordx4 v[70:73], v[68:69], off
	global_load_dwordx4 v[218:221], v[68:69], off offset:256
	global_load_dwordx4 v[222:225], v[66:67], off
	global_load_dwordx4 v[226:229], v[66:67], off offset:256
	s_and_b64 vcc, exec, s[36:37]
	s_waitcnt vmcnt(3)
	v_lshlrev_b32_e32 v0, 16, v70
	v_mul_f32_e32 v0, 0xbfb8aa3b, v0
	v_exp_f32_e32 v0, v0
	s_nop 0
	v_add_f32_e32 v0, 1.0, v0
	v_rcp_f32_e32 v74, v0
	v_and_b32_e32 v0, 0xffff0000, v70
	v_mul_f32_e32 v0, 0xbfb8aa3b, v0
	v_exp_f32_e32 v0, v0
	s_nop 0
	v_add_f32_e32 v0, 1.0, v0
	v_rcp_f32_e32 v75, v0
	v_lshlrev_b32_e32 v0, 16, v71
	v_mul_f32_e32 v0, 0xbfb8aa3b, v0
	v_exp_f32_e32 v0, v0
	v_pk_mul_f32 v[62:63], v[62:63], v[74:75]
	v_add_f32_e32 v0, 1.0, v0
	v_rcp_f32_e32 v70, v0
	v_and_b32_e32 v0, 0xffff0000, v71
	v_mul_f32_e32 v0, 0xbfb8aa3b, v0
	v_exp_f32_e32 v0, v0
	s_nop 0
	v_add_f32_e32 v0, 1.0, v0
	v_rcp_f32_e32 v71, v0
	v_lshlrev_b32_e32 v0, 16, v72
	v_mul_f32_e32 v0, 0xbfb8aa3b, v0
	v_exp_f32_e32 v0, v0
	v_pk_mul_f32 v[64:65], v[64:65], v[70:71]
	v_add_f32_e32 v0, 1.0, v0
	v_rcp_f32_e32 v70, v0
	v_and_b32_e32 v0, 0xffff0000, v72
	v_mul_f32_e32 v0, 0xbfb8aa3b, v0
	v_exp_f32_e32 v0, v0
	s_nop 0
	v_add_f32_e32 v0, 1.0, v0
	v_rcp_f32_e32 v71, v0
	v_lshlrev_b32_e32 v0, 16, v73
	v_mul_f32_e32 v0, 0xbfb8aa3b, v0
	v_exp_f32_e32 v0, v0
	v_pk_mul_f32 v[58:59], v[58:59], v[70:71]
	v_add_f32_e32 v0, 1.0, v0
	v_rcp_f32_e32 v70, v0
	v_and_b32_e32 v0, 0xffff0000, v73
	v_mul_f32_e32 v0, 0xbfb8aa3b, v0
	v_exp_f32_e32 v0, v0
	s_nop 0
	v_add_f32_e32 v0, 1.0, v0
	v_rcp_f32_e32 v71, v0
	s_nop 0
	v_pk_mul_f32 v[60:61], v[60:61], v[70:71]
	s_cbranch_vccnz .LBB0_161
	s_waitcnt vmcnt(1)
	v_mov_b32_e32 v70, v222
	v_mov_b32_e32 v71, v223
	v_mov_b32_e32 v72, v224
	v_mov_b32_e32 v73, v225
	v_lshlrev_b32_e32 v74, 16, v70
	v_and_b32_e32 v75, 0xffff0000, v70
	v_lshlrev_b32_e32 v70, 16, v71
	v_and_b32_e32 v71, 0xffff0000, v71
	v_pk_add_f32 v[64:65], v[64:65], v[70:71]
	v_lshlrev_b32_e32 v70, 16, v72
	v_and_b32_e32 v71, 0xffff0000, v72
	v_pk_add_f32 v[58:59], v[58:59], v[70:71]
	v_lshlrev_b32_e32 v70, 16, v73
	v_and_b32_e32 v71, 0xffff0000, v73
	v_pk_add_f32 v[62:63], v[62:63], v[74:75]
	v_pk_add_f32 v[60:61], v[60:61], v[70:71]
.LBB0_161:
	v_cvt_pk_bf16_f32 v62, v62, v63
	v_cvt_pk_bf16_f32 v63, v64, v65
	v_cvt_pk_bf16_f32 v64, v58, v59
	s_nop 0
	v_cvt_pk_bf16_f32 v65, v60, v61
	global_store_dwordx4 v[66:67], v[62:65], off
	s_and_b64 vcc, exec, s[36:37]
	s_waitcnt vmcnt(2)
	v_mov_b32_e32 v58, v218
	v_mov_b32_e32 v59, v219
	v_mov_b32_e32 v60, v220
	v_mov_b32_e32 v61, v221
	v_lshlrev_b32_e32 v0, 16, v58
	v_and_b32_e32 v58, 0xffff0000, v58
	v_lshlrev_b32_e32 v62, 16, v59
	v_and_b32_e32 v59, 0xffff0000, v59
	v_lshlrev_b32_e32 v63, 16, v60
	v_and_b32_e32 v60, 0xffff0000, v60
	v_lshlrev_b32_e32 v64, 16, v61
	v_and_b32_e32 v61, 0xffff0000, v61
	v_mul_f32_e32 v0, 0xbfb8aa3b, v0
	v_mul_f32_e32 v58, 0xbfb8aa3b, v58
	v_mul_f32_e32 v62, 0xbfb8aa3b, v62
	v_mul_f32_e32 v59, 0xbfb8aa3b, v59
	v_mul_f32_e32 v63, 0xbfb8aa3b, v63
	v_mul_f32_e32 v60, 0xbfb8aa3b, v60
	v_mul_f32_e32 v64, 0xbfb8aa3b, v64
	v_mul_f32_e32 v61, 0xbfb8aa3b, v61
	v_exp_f32_e32 v0, v0
	v_exp_f32_e32 v58, v58
	v_exp_f32_e32 v62, v62
	v_exp_f32_e32 v59, v59
	v_exp_f32_e32 v63, v63
	v_exp_f32_e32 v60, v60
	v_exp_f32_e32 v64, v64
	v_exp_f32_e32 v61, v61
	v_add_f32_e32 v0, 1.0, v0
	v_add_f32_e32 v65, 1.0, v58
	v_add_f32_e32 v62, 1.0, v62
	v_add_f32_e32 v68, 1.0, v59
	v_add_f32_e32 v63, 1.0, v63
	v_add_f32_e32 v69, 1.0, v60
	v_add_f32_e32 v64, 1.0, v64
	v_add_f32_e32 v70, 1.0, v61
	v_rcp_f32_e32 v58, v0
	v_rcp_f32_e32 v59, v65
	v_rcp_f32_e32 v60, v62
	v_rcp_f32_e32 v61, v68
	v_rcp_f32_e32 v62, v63
	v_rcp_f32_e32 v63, v69
	v_rcp_f32_e32 v64, v64
	v_rcp_f32_e32 v65, v70
	v_pk_mul_f32 v[54:55], v[54:55], v[58:59]
	v_pk_mul_f32 v[56:57], v[56:57], v[60:61]
	v_pk_mul_f32 v[58:59], v[50:51], v[62:63]
	v_pk_mul_f32 v[50:51], v[52:53], v[64:65]
	s_cbranch_vccnz .LBB0_163
	s_waitcnt vmcnt(0)
	v_mov_b32_e32 v60, v226
	v_mov_b32_e32 v61, v227
	v_mov_b32_e32 v62, v228
	v_mov_b32_e32 v63, v229
	v_lshlrev_b32_e32 v52, 16, v60
	v_and_b32_e32 v53, 0xffff0000, v60
	v_pk_add_f32 v[54:55], v[54:55], v[52:53]
	v_lshlrev_b32_e32 v52, 16, v61
	v_and_b32_e32 v53, 0xffff0000, v61
	v_pk_add_f32 v[56:57], v[56:57], v[52:53]
	v_lshlrev_b32_e32 v52, 16, v62
	v_and_b32_e32 v53, 0xffff0000, v62
	v_pk_add_f32 v[58:59], v[58:59], v[52:53]
	v_lshlrev_b32_e32 v52, 16, v63
	v_and_b32_e32 v53, 0xffff0000, v63
	v_pk_add_f32 v[50:51], v[50:51], v[52:53]
; DI float bflo(unsigned w) { return __uint_as_float(w << 16); }
; DI float bfhi(unsigned w) { return __uint_as_float(w & 0xffff0000u); }
; DI unsigned cvtpk(float lo, float hi) { unsigned r; asm volatile("v_cvt_pk_bf16_f32 %0, %1, %2" : "=v"(r) : "v"(lo), "v"(hi)); return r; }
; DI float sigmoidf_(float x) { return __builtin_amdgcn_rcpf(1.f + __expf(-x)); }
;     __device__ __forceinline__ void operator()(const f32x4 (&acc)[2][2][4][2], const Unit& u, int wr, int wc, int fr, int fq) const {
;     ...
;                 const int row = u.pm * BM + ai * HALF + wr * 64 + m * 16 + fr;
;                 const int colb = pn * BM + wc * 32 + 8 * fq;
;                 const unsigned goff = (unsigned)(row * LDP + C_GT + br * 1024 + colb), ooff = (unsigned)(row * 1024 + colb);
;                 const bf16_t* gp = proj + goff;
;                 bf16_t* op = out + ooff;
;                 __builtin_amdgcn_sched_barrier(0);
; #pragma unroll
;                 for (int bj = 0; bj < 2; ++bj) {
;                     const u32x4 g = *(const u32x4*)(gp + bj * HALF);
;                     f32x4 v0 = acc[ai][bj][m][0], v1 = acc[ai][bj][m][1];
;                     v0[0] *= sigmoidf_(bflo(g[0])); v0[1] *= sigmoidf_(bfhi(g[0])); v0[2] *= sigmoidf_(bflo(g[1])); v0[3] *= sigmoidf_(bfhi(g[1]));
;                     v1[0] *= sigmoidf_(bflo(g[2])); v1[1] *= sigmoidf_(bfhi(g[2])); v1[2] *= sigmoidf_(bflo(g[3])); v1[3] *= sigmoidf_(bfhi(g[3]));
;                     if (br > 0) {
;                         const u32x4 o = *(const u32x4*)(op + bj * HALF);
;                         v0[0] += bflo(o[0]); v0[1] += bfhi(o[0]); v0[2] += bflo(o[1]); v0[3] += bfhi(o[1]);
;                         v1[0] += bflo(o[2]); v1[1] += bfhi(o[2]); v1[2] += bflo(o[3]); v1[3] += bfhi(o[3]);
;                     }
;                     u32x4 w = {cvtpk(v0[0], v0[1]), cvtpk(v0[2], v0[3]), cvtpk(v1[0], v1[1]), cvtpk(v1[2], v1[3])};
;                     *(u32x4*)(op + bj * HALF) = w;
.LBB0_163:
	v_readlane_b32 s80, v255, 8
	v_cvt_pk_bf16_f32 v52, v54, v55
	v_cvt_pk_bf16_f32 v53, v56, v57
	v_cvt_pk_bf16_f32 v54, v58, v59
	v_cvt_pk_bf16_f32 v55, v50, v51
	v_add_u32_e32 v0, v167, v158
	v_or_b32_e32 v50, v166, v159
	v_readlane_b32 s92, v255, 20
	v_readlane_b32 s93, v255, 21
	v_readlane_b32 s94, v255, 22
	v_readlane_b32 s95, v255, 23
	v_mov_b32_e32 v51, v1
	global_store_dwordx4 v[66:67], v[52:55], off offset:256
	v_lshl_add_u64 v[50:51], v[50:51], 1, s[92:93]
	v_readlane_b32 s81, v255, 9
	v_lshl_add_u64 v[52:53], v[0:1], 1, s[94:95]
	v_readlane_b32 s82, v255, 10
	v_readlane_b32 s83, v255, 11
	v_readlane_b32 s84, v255, 12
	v_readlane_b32 s85, v255, 13
	v_readlane_b32 s86, v255, 14
	v_readlane_b32 s87, v255, 15
	v_readlane_b32 s88, v255, 16
	v_readlane_b32 s89, v255, 17
	v_readlane_b32 s90, v255, 18
	v_readlane_b32 s91, v255, 19
	global_load_dwordx4 v[54:57], v[52:53], off
	global_load_dwordx4 v[218:221], v[52:53], off offset:256
	global_load_dwordx4 v[222:225], v[50:51], off
	global_load_dwordx4 v[226:229], v[50:51], off offset:256
	s_and_b64 vcc, exec, s[36:37]
	s_waitcnt vmcnt(3)
	v_lshlrev_b32_e32 v0, 16, v54
	v_mul_f32_e32 v0, 0xbfb8aa3b, v0
	v_exp_f32_e32 v0, v0
	s_nop 0
	v_add_f32_e32 v0, 1.0, v0
	v_rcp_f32_e32 v58, v0
	v_and_b32_e32 v0, 0xffff0000, v54
	v_mul_f32_e32 v0, 0xbfb8aa3b, v0
	v_exp_f32_e32 v0, v0
	s_nop 0
	v_add_f32_e32 v0, 1.0, v0
	v_rcp_f32_e32 v59, v0
	v_lshlrev_b32_e32 v0, 16, v55
	v_mul_f32_e32 v0, 0xbfb8aa3b, v0
	v_exp_f32_e32 v0, v0
	v_pk_mul_f32 v[46:47], v[46:47], v[58:59]
	v_add_f32_e32 v0, 1.0, v0
	v_rcp_f32_e32 v54, v0
	v_and_b32_e32 v0, 0xffff0000, v55
	v_mul_f32_e32 v0, 0xbfb8aa3b, v0
	v_exp_f32_e32 v0, v0
	s_nop 0
	v_add_f32_e32 v0, 1.0, v0
	v_rcp_f32_e32 v55, v0
	v_lshlrev_b32_e32 v0, 16, v56
	v_mul_f32_e32 v0, 0xbfb8aa3b, v0
	v_exp_f32_e32 v0, v0
	v_pk_mul_f32 v[48:49], v[48:49], v[54:55]
	v_add_f32_e32 v0, 1.0, v0
	v_rcp_f32_e32 v54, v0
	v_and_b32_e32 v0, 0xffff0000, v56
	v_mul_f32_e32 v0, 0xbfb8aa3b, v0
	v_exp_f32_e32 v0, v0
	s_nop 0
	v_add_f32_e32 v0, 1.0, v0
	v_rcp_f32_e32 v55, v0
	v_lshlrev_b32_e32 v0, 16, v57
	v_mul_f32_e32 v0, 0xbfb8aa3b, v0
	v_exp_f32_e32 v0, v0
	v_pk_mul_f32 v[42:43], v[42:43], v[54:55]
	v_add_f32_e32 v0, 1.0, v0
	v_rcp_f32_e32 v54, v0
	v_and_b32_e32 v0, 0xffff0000, v57
	v_mul_f32_e32 v0, 0xbfb8aa3b, v0
	v_exp_f32_e32 v0, v0
	s_nop 0
	v_add_f32_e32 v0, 1.0, v0
	v_rcp_f32_e32 v55, v0
	s_nop 0
	v_pk_mul_f32 v[44:45], v[44:45], v[54:55]
	s_cbranch_vccnz .LBB0_165
	s_waitcnt vmcnt(1)
	v_mov_b32_e32 v54, v222
	v_mov_b32_e32 v55, v223
	v_mov_b32_e32 v56, v224
	v_mov_b32_e32 v57, v225
	v_lshlrev_b32_e32 v58, 16, v54
	v_and_b32_e32 v59, 0xffff0000, v54
	v_lshlrev_b32_e32 v54, 16, v55
	v_and_b32_e32 v55, 0xffff0000, v55
	v_pk_add_f32 v[48:49], v[48:49], v[54:55]
	v_lshlrev_b32_e32 v54, 16, v56
	v_and_b32_e32 v55, 0xffff0000, v56
	v_pk_add_f32 v[42:43], v[42:43], v[54:55]
	v_lshlrev_b32_e32 v54, 16, v57
	v_and_b32_e32 v55, 0xffff0000, v57
	v_pk_add_f32 v[46:47], v[46:47], v[58:59]
	v_pk_add_f32 v[44:45], v[44:45], v[54:55]
.LBB0_165:
	v_cvt_pk_bf16_f32 v46, v46, v47
	v_cvt_pk_bf16_f32 v47, v48, v49
	v_cvt_pk_bf16_f32 v48, v42, v43
	s_nop 0
	v_cvt_pk_bf16_f32 v49, v44, v45
	global_store_dwordx4 v[50:51], v[46:49], off
	s_and_b64 vcc, exec, s[36:37]
	s_waitcnt vmcnt(2)
	v_mov_b32_e32 v42, v218
	v_mov_b32_e32 v43, v219
	v_mov_b32_e32 v44, v220
	v_mov_b32_e32 v45, v221
	v_lshlrev_b32_e32 v0, 16, v42
	v_and_b32_e32 v42, 0xffff0000, v42
	v_lshlrev_b32_e32 v46, 16, v43
	v_and_b32_e32 v43, 0xffff0000, v43
	v_lshlrev_b32_e32 v47, 16, v44
	v_and_b32_e32 v44, 0xffff0000, v44
	v_lshlrev_b32_e32 v48, 16, v45
	v_and_b32_e32 v45, 0xffff0000, v45
	v_mul_f32_e32 v0, 0xbfb8aa3b, v0
	v_mul_f32_e32 v42, 0xbfb8aa3b, v42
	v_mul_f32_e32 v46, 0xbfb8aa3b, v46
	v_mul_f32_e32 v43, 0xbfb8aa3b, v43
	v_mul_f32_e32 v47, 0xbfb8aa3b, v47
	v_mul_f32_e32 v44, 0xbfb8aa3b, v44
	v_mul_f32_e32 v48, 0xbfb8aa3b, v48
	v_mul_f32_e32 v45, 0xbfb8aa3b, v45
	v_exp_f32_e32 v0, v0
	v_exp_f32_e32 v42, v42
	v_exp_f32_e32 v46, v46
	v_exp_f32_e32 v43, v43
	v_exp_f32_e32 v47, v47
	v_exp_f32_e32 v44, v44
	v_exp_f32_e32 v48, v48
	v_exp_f32_e32 v45, v45
	v_add_f32_e32 v0, 1.0, v0
	v_add_f32_e32 v49, 1.0, v42
	v_add_f32_e32 v46, 1.0, v46
	v_add_f32_e32 v52, 1.0, v43
	v_add_f32_e32 v47, 1.0, v47
	v_add_f32_e32 v53, 1.0, v44
	v_add_f32_e32 v48, 1.0, v48
	v_add_f32_e32 v54, 1.0, v45
	v_rcp_f32_e32 v42, v0
	v_rcp_f32_e32 v43, v49
	v_rcp_f32_e32 v44, v46
	v_rcp_f32_e32 v45, v52
	v_rcp_f32_e32 v46, v47
	v_rcp_f32_e32 v47, v53
	v_rcp_f32_e32 v48, v48
	v_rcp_f32_e32 v49, v54
	v_pk_mul_f32 v[38:39], v[38:39], v[42:43]
	v_pk_mul_f32 v[40:41], v[40:41], v[44:45]
	v_pk_mul_f32 v[42:43], v[34:35], v[46:47]
	v_pk_mul_f32 v[34:35], v[36:37], v[48:49]
	s_cbranch_vccnz .LBB0_167
	s_waitcnt vmcnt(0)
	v_mov_b32_e32 v44, v226
	v_mov_b32_e32 v45, v227
	v_mov_b32_e32 v46, v228
	v_mov_b32_e32 v47, v229
	v_lshlrev_b32_e32 v36, 16, v44
	v_and_b32_e32 v37, 0xffff0000, v44
	v_pk_add_f32 v[38:39], v[38:39], v[36:37]
	v_lshlrev_b32_e32 v36, 16, v45
	v_and_b32_e32 v37, 0xffff0000, v45
	v_pk_add_f32 v[40:41], v[40:41], v[36:37]
	v_lshlrev_b32_e32 v36, 16, v46
	v_and_b32_e32 v37, 0xffff0000, v46
	v_pk_add_f32 v[42:43], v[42:43], v[36:37]
	v_lshlrev_b32_e32 v36, 16, v47
	v_and_b32_e32 v37, 0xffff0000, v47
	v_pk_add_f32 v[34:35], v[34:35], v[36:37]
; DI float bflo(unsigned w) { return __uint_as_float(w << 16); }
; DI float bfhi(unsigned w) { return __uint_as_float(w & 0xffff0000u); }
; DI unsigned cvtpk(float lo, float hi) { unsigned r; asm volatile("v_cvt_pk_bf16_f32 %0, %1, %2" : "=v"(r) : "v"(lo), "v"(hi)); return r; }
; DI float sigmoidf_(float x) { return __builtin_amdgcn_rcpf(1.f + __expf(-x)); }
;     __device__ __forceinline__ void operator()(const f32x4 (&acc)[2][2][4][2], const Unit& u, int wr, int wc, int fr, int fq) const {
;     ...
;                 const int row = u.pm * BM + ai * HALF + wr * 64 + m * 16 + fr;
;                 const int colb = pn * BM + wc * 32 + 8 * fq;
;                 const unsigned goff = (unsigned)(row * LDP + C_GT + br * 1024 + colb), ooff = (unsigned)(row * 1024 + colb);
;                 const bf16_t* gp = proj + goff;
;                 bf16_t* op = out + ooff;
;                 __builtin_amdgcn_sched_barrier(0);
; #pragma unroll
;                 for (int bj = 0; bj < 2; ++bj) {
;                     const u32x4 g = *(const u32x4*)(gp + bj * HALF);
;                     f32x4 v0 = acc[ai][bj][m][0], v1 = acc[ai][bj][m][1];
;                     v0[0] *= sigmoidf_(bflo(g[0])); v0[1] *= sigmoidf_(bfhi(g[0])); v0[2] *= sigmoidf_(bflo(g[1])); v0[3] *= sigmoidf_(bfhi(g[1]));
;                     v1[0] *= sigmoidf_(bflo(g[2])); v1[1] *= sigmoidf_(bfhi(g[2])); v1[2] *= sigmoidf_(bflo(g[3])); v1[3] *= sigmoidf_(bfhi(g[3]));
;                     if (br > 0) {
;                         const u32x4 o = *(const u32x4*)(op + bj * HALF);
;                         v0[0] += bflo(o[0]); v0[1] += bfhi(o[0]); v0[2] += bflo(o[1]); v0[3] += bfhi(o[1]);
;                         v1[0] += bflo(o[2]); v1[1] += bfhi(o[2]); v1[2] += bflo(o[3]); v1[3] += bfhi(o[3]);
;                     }
;                     u32x4 w = {cvtpk(v0[0], v0[1]), cvtpk(v0[2], v0[3]), cvtpk(v1[0], v1[1]), cvtpk(v1[2], v1[3])};
;                     *(u32x4*)(op + bj * HALF) = w;
.LBB0_167:
	v_readlane_b32 s80, v255, 8
	v_cvt_pk_bf16_f32 v36, v38, v39
	v_cvt_pk_bf16_f32 v37, v40, v41
	v_cvt_pk_bf16_f32 v38, v42, v43
	v_cvt_pk_bf16_f32 v39, v34, v35
	v_add_u32_e32 v0, v167, v160
	v_or_b32_e32 v34, v166, v161
	v_readlane_b32 s92, v255, 20
	v_readlane_b32 s93, v255, 21
	v_readlane_b32 s94, v255, 22
	v_readlane_b32 s95, v255, 23
	v_mov_b32_e32 v35, v1
	global_store_dwordx4 v[50:51], v[36:39], off offset:256
	v_lshl_add_u64 v[34:35], v[34:35], 1, s[92:93]
	v_readlane_b32 s81, v255, 9
	v_lshl_add_u64 v[36:37], v[0:1], 1, s[94:95]
	v_readlane_b32 s82, v255, 10
	v_readlane_b32 s83, v255, 11
	v_readlane_b32 s84, v255, 12
	v_readlane_b32 s85, v255, 13
	v_readlane_b32 s86, v255, 14
	v_readlane_b32 s87, v255, 15
	v_readlane_b32 s88, v255, 16
	v_readlane_b32 s89, v255, 17
	v_readlane_b32 s90, v255, 18
	v_readlane_b32 s91, v255, 19
	global_load_dwordx4 v[38:41], v[36:37], off
	global_load_dwordx4 v[218:221], v[36:37], off offset:256
	global_load_dwordx4 v[222:225], v[34:35], off
	global_load_dwordx4 v[226:229], v[34:35], off offset:256
	s_and_b64 vcc, exec, s[36:37]
	s_waitcnt vmcnt(3)
	v_lshlrev_b32_e32 v0, 16, v38
	v_mul_f32_e32 v0, 0xbfb8aa3b, v0
	v_exp_f32_e32 v0, v0
	s_nop 0
	v_add_f32_e32 v0, 1.0, v0
	v_rcp_f32_e32 v42, v0
	v_and_b32_e32 v0, 0xffff0000, v38
	v_mul_f32_e32 v0, 0xbfb8aa3b, v0
	v_exp_f32_e32 v0, v0
	s_nop 0
	v_add_f32_e32 v0, 1.0, v0
	v_rcp_f32_e32 v43, v0
	v_lshlrev_b32_e32 v0, 16, v39
	v_mul_f32_e32 v0, 0xbfb8aa3b, v0
	v_exp_f32_e32 v0, v0
	v_pk_mul_f32 v[30:31], v[30:31], v[42:43]
	v_add_f32_e32 v0, 1.0, v0
	v_rcp_f32_e32 v38, v0
	v_and_b32_e32 v0, 0xffff0000, v39
	v_mul_f32_e32 v0, 0xbfb8aa3b, v0
	v_exp_f32_e32 v0, v0
	s_nop 0
	v_add_f32_e32 v0, 1.0, v0
	v_rcp_f32_e32 v39, v0
	v_lshlrev_b32_e32 v0, 16, v40
	v_mul_f32_e32 v0, 0xbfb8aa3b, v0
	v_exp_f32_e32 v0, v0
	v_pk_mul_f32 v[32:33], v[32:33], v[38:39]
	v_add_f32_e32 v0, 1.0, v0
	v_rcp_f32_e32 v38, v0
	v_and_b32_e32 v0, 0xffff0000, v40
	v_mul_f32_e32 v0, 0xbfb8aa3b, v0
	v_exp_f32_e32 v0, v0
	s_nop 0
	v_add_f32_e32 v0, 1.0, v0
	v_rcp_f32_e32 v39, v0
	v_lshlrev_b32_e32 v0, 16, v41
	v_mul_f32_e32 v0, 0xbfb8aa3b, v0
	v_exp_f32_e32 v0, v0
	v_pk_mul_f32 v[26:27], v[26:27], v[38:39]
	v_add_f32_e32 v0, 1.0, v0
	v_rcp_f32_e32 v38, v0
	v_and_b32_e32 v0, 0xffff0000, v41
	v_mul_f32_e32 v0, 0xbfb8aa3b, v0
	v_exp_f32_e32 v0, v0
	s_nop 0
	v_add_f32_e32 v0, 1.0, v0
	v_rcp_f32_e32 v39, v0
	s_nop 0
	v_pk_mul_f32 v[28:29], v[28:29], v[38:39]
	s_cbranch_vccnz .LBB0_169
	s_waitcnt vmcnt(1)
	v_mov_b32_e32 v38, v222
	v_mov_b32_e32 v39, v223
	v_mov_b32_e32 v40, v224
	v_mov_b32_e32 v41, v225
	v_lshlrev_b32_e32 v42, 16, v38
	v_and_b32_e32 v43, 0xffff0000, v38
	v_lshlrev_b32_e32 v38, 16, v39
	v_and_b32_e32 v39, 0xffff0000, v39
	v_pk_add_f32 v[32:33], v[32:33], v[38:39]
	v_lshlrev_b32_e32 v38, 16, v40
	v_and_b32_e32 v39, 0xffff0000, v40
	v_pk_add_f32 v[26:27], v[26:27], v[38:39]
	v_lshlrev_b32_e32 v38, 16, v41
	v_and_b32_e32 v39, 0xffff0000, v41
	v_pk_add_f32 v[30:31], v[30:31], v[42:43]
	v_pk_add_f32 v[28:29], v[28:29], v[38:39]
.LBB0_169:
	v_cvt_pk_bf16_f32 v30, v30, v31
	v_cvt_pk_bf16_f32 v31, v32, v33
	v_cvt_pk_bf16_f32 v32, v26, v27
	s_nop 0
	v_cvt_pk_bf16_f32 v33, v28, v29
	global_store_dwordx4 v[34:35], v[30:33], off
	s_and_b64 vcc, exec, s[36:37]
	s_waitcnt vmcnt(2)
	v_mov_b32_e32 v26, v218
	v_mov_b32_e32 v27, v219
	v_mov_b32_e32 v28, v220
	v_mov_b32_e32 v29, v221
	v_lshlrev_b32_e32 v0, 16, v26
	v_and_b32_e32 v26, 0xffff0000, v26
	v_lshlrev_b32_e32 v30, 16, v27
	v_and_b32_e32 v27, 0xffff0000, v27
	v_lshlrev_b32_e32 v31, 16, v28
	v_and_b32_e32 v28, 0xffff0000, v28
	v_lshlrev_b32_e32 v32, 16, v29
	v_and_b32_e32 v29, 0xffff0000, v29
	v_mul_f32_e32 v0, 0xbfb8aa3b, v0
	v_mul_f32_e32 v26, 0xbfb8aa3b, v26
	v_mul_f32_e32 v30, 0xbfb8aa3b, v30
	v_mul_f32_e32 v27, 0xbfb8aa3b, v27
	v_mul_f32_e32 v31, 0xbfb8aa3b, v31
	v_mul_f32_e32 v28, 0xbfb8aa3b, v28
	v_mul_f32_e32 v32, 0xbfb8aa3b, v32
	v_mul_f32_e32 v29, 0xbfb8aa3b, v29
	v_exp_f32_e32 v0, v0
	v_exp_f32_e32 v26, v26
	v_exp_f32_e32 v30, v30
	v_exp_f32_e32 v27, v27
	v_exp_f32_e32 v31, v31
	v_exp_f32_e32 v28, v28
	v_exp_f32_e32 v32, v32
	v_exp_f32_e32 v29, v29
	v_add_f32_e32 v0, 1.0, v0
	v_add_f32_e32 v33, 1.0, v26
	v_add_f32_e32 v30, 1.0, v30
	v_add_f32_e32 v36, 1.0, v27
	v_add_f32_e32 v31, 1.0, v31
	v_add_f32_e32 v37, 1.0, v28
	v_add_f32_e32 v32, 1.0, v32
	v_add_f32_e32 v38, 1.0, v29
	v_rcp_f32_e32 v26, v0
	v_rcp_f32_e32 v27, v33
	v_rcp_f32_e32 v28, v30
	v_rcp_f32_e32 v29, v36
	v_rcp_f32_e32 v30, v31
	v_rcp_f32_e32 v31, v37
	v_rcp_f32_e32 v32, v32
	v_rcp_f32_e32 v33, v38
	v_pk_mul_f32 v[22:23], v[22:23], v[26:27]
	v_pk_mul_f32 v[24:25], v[24:25], v[28:29]
	v_pk_mul_f32 v[26:27], v[18:19], v[30:31]
	v_pk_mul_f32 v[18:19], v[20:21], v[32:33]
	s_cbranch_vccnz .LBB0_171
	s_waitcnt vmcnt(0)
	v_mov_b32_e32 v28, v226
	v_mov_b32_e32 v29, v227
	v_mov_b32_e32 v30, v228
	v_mov_b32_e32 v31, v229
	v_lshlrev_b32_e32 v20, 16, v28
	v_and_b32_e32 v21, 0xffff0000, v28
	v_pk_add_f32 v[22:23], v[22:23], v[20:21]
	v_lshlrev_b32_e32 v20, 16, v29
	v_and_b32_e32 v21, 0xffff0000, v29
	v_pk_add_f32 v[24:25], v[24:25], v[20:21]
	v_lshlrev_b32_e32 v20, 16, v30
	v_and_b32_e32 v21, 0xffff0000, v30
	v_pk_add_f32 v[26:27], v[26:27], v[20:21]
	v_lshlrev_b32_e32 v20, 16, v31
	v_and_b32_e32 v21, 0xffff0000, v31
	v_pk_add_f32 v[18:19], v[18:19], v[20:21]
; DI float bflo(unsigned w) { return __uint_as_float(w << 16); }
; DI float bfhi(unsigned w) { return __uint_as_float(w & 0xffff0000u); }
; DI unsigned cvtpk(float lo, float hi) { unsigned r; asm volatile("v_cvt_pk_bf16_f32 %0, %1, %2" : "=v"(r) : "v"(lo), "v"(hi)); return r; }
; DI float sigmoidf_(float x) { return __builtin_amdgcn_rcpf(1.f + __expf(-x)); }
;     __device__ __forceinline__ void operator()(const f32x4 (&acc)[2][2][4][2], const Unit& u, int wr, int wc, int fr, int fq) const {
;     ...
;                 const int row = u.pm * BM + ai * HALF + wr * 64 + m * 16 + fr;
;                 const int colb = pn * BM + wc * 32 + 8 * fq;
;                 const unsigned goff = (unsigned)(row * LDP + C_GT + br * 1024 + colb), ooff = (unsigned)(row * 1024 + colb);
;                 const bf16_t* gp = proj + goff;
;                 bf16_t* op = out + ooff;
;                 __builtin_amdgcn_sched_barrier(0);
; #pragma unroll
;                 for (int bj = 0; bj < 2; ++bj) {
;                     const u32x4 g = *(const u32x4*)(gp + bj * HALF);
;                     f32x4 v0 = acc[ai][bj][m][0], v1 = acc[ai][bj][m][1];
;                     v0[0] *= sigmoidf_(bflo(g[0])); v0[1] *= sigmoidf_(bfhi(g[0])); v0[2] *= sigmoidf_(bflo(g[1])); v0[3] *= sigmoidf_(bfhi(g[1]));
;                     v1[0] *= sigmoidf_(bflo(g[2])); v1[1] *= sigmoidf_(bfhi(g[2])); v1[2] *= sigmoidf_(bflo(g[3])); v1[3] *= sigmoidf_(bfhi(g[3]));
;                     if (br > 0) {
;                         const u32x4 o = *(const u32x4*)(op + bj * HALF);
;                         v0[0] += bflo(o[0]); v0[1] += bfhi(o[0]); v0[2] += bflo(o[1]); v0[3] += bfhi(o[1]);
;                         v1[0] += bflo(o[2]); v1[1] += bfhi(o[2]); v1[2] += bflo(o[3]); v1[3] += bfhi(o[3]);
;                     }
;                     u32x4 w = {cvtpk(v0[0], v0[1]), cvtpk(v0[2], v0[3]), cvtpk(v1[0], v1[1]), cvtpk(v1[2], v1[3])};
;                     *(u32x4*)(op + bj * HALF) = w;
.LBB0_171:
	v_readlane_b32 s80, v255, 8
	v_cvt_pk_bf16_f32 v20, v22, v23
	v_cvt_pk_bf16_f32 v21, v24, v25
	v_cvt_pk_bf16_f32 v22, v26, v27
	v_cvt_pk_bf16_f32 v23, v18, v19
	v_add_u32_e32 v0, v167, v162
	v_or_b32_e32 v18, v166, v163
	v_readlane_b32 s92, v255, 20
	v_readlane_b32 s93, v255, 21
	v_readlane_b32 s94, v255, 22
	v_readlane_b32 s95, v255, 23
	v_mov_b32_e32 v19, v1
	global_store_dwordx4 v[34:35], v[20:23], off offset:256
	v_lshl_add_u64 v[18:19], v[18:19], 1, s[92:93]
	v_readlane_b32 s81, v255, 9
	v_lshl_add_u64 v[20:21], v[0:1], 1, s[94:95]
	v_readlane_b32 s82, v255, 10
	v_readlane_b32 s83, v255, 11
	v_readlane_b32 s84, v255, 12
	v_readlane_b32 s85, v255, 13
	v_readlane_b32 s86, v255, 14
	v_readlane_b32 s87, v255, 15
	v_readlane_b32 s88, v255, 16
	v_readlane_b32 s89, v255, 17
	v_readlane_b32 s90, v255, 18
	v_readlane_b32 s91, v255, 19
	global_load_dwordx4 v[22:25], v[20:21], off
	global_load_dwordx4 v[218:221], v[20:21], off offset:256
	global_load_dwordx4 v[222:225], v[18:19], off
	global_load_dwordx4 v[226:229], v[18:19], off offset:256
	s_and_b64 vcc, exec, s[36:37]
	s_waitcnt vmcnt(3)
	v_lshlrev_b32_e32 v0, 16, v22
	v_mul_f32_e32 v0, 0xbfb8aa3b, v0
	v_exp_f32_e32 v0, v0
	s_nop 0
	v_add_f32_e32 v0, 1.0, v0
	v_rcp_f32_e32 v26, v0
	v_and_b32_e32 v0, 0xffff0000, v22
	v_mul_f32_e32 v0, 0xbfb8aa3b, v0
	v_exp_f32_e32 v0, v0
	s_nop 0
	v_add_f32_e32 v0, 1.0, v0
	v_rcp_f32_e32 v27, v0
	v_lshlrev_b32_e32 v0, 16, v23
	v_mul_f32_e32 v0, 0xbfb8aa3b, v0
	v_exp_f32_e32 v0, v0
	v_pk_mul_f32 v[14:15], v[14:15], v[26:27]
	v_add_f32_e32 v0, 1.0, v0
	v_rcp_f32_e32 v22, v0
	v_and_b32_e32 v0, 0xffff0000, v23
	v_mul_f32_e32 v0, 0xbfb8aa3b, v0
	v_exp_f32_e32 v0, v0
	s_nop 0
	v_add_f32_e32 v0, 1.0, v0
	v_rcp_f32_e32 v23, v0
	v_lshlrev_b32_e32 v0, 16, v24
	v_mul_f32_e32 v0, 0xbfb8aa3b, v0
	v_exp_f32_e32 v0, v0
	v_pk_mul_f32 v[16:17], v[16:17], v[22:23]
	v_add_f32_e32 v0, 1.0, v0
	v_rcp_f32_e32 v22, v0
	v_and_b32_e32 v0, 0xffff0000, v24
	v_mul_f32_e32 v0, 0xbfb8aa3b, v0
	v_exp_f32_e32 v0, v0
	s_nop 0
	v_add_f32_e32 v0, 1.0, v0
	v_rcp_f32_e32 v23, v0
	v_lshlrev_b32_e32 v0, 16, v25
	v_mul_f32_e32 v0, 0xbfb8aa3b, v0
	v_exp_f32_e32 v0, v0
	v_pk_mul_f32 v[10:11], v[10:11], v[22:23]
	v_add_f32_e32 v0, 1.0, v0
	v_rcp_f32_e32 v22, v0
	v_and_b32_e32 v0, 0xffff0000, v25
	v_mul_f32_e32 v0, 0xbfb8aa3b, v0
	v_exp_f32_e32 v0, v0
	s_nop 0
	v_add_f32_e32 v0, 1.0, v0
	v_rcp_f32_e32 v23, v0
	s_nop 0
	v_pk_mul_f32 v[12:13], v[12:13], v[22:23]
	s_cbranch_vccnz .LBB0_173
	s_waitcnt vmcnt(1)
	v_mov_b32_e32 v22, v222
	v_mov_b32_e32 v23, v223
	v_mov_b32_e32 v24, v224
	v_mov_b32_e32 v25, v225
	v_lshlrev_b32_e32 v26, 16, v22
	v_and_b32_e32 v27, 0xffff0000, v22
	v_lshlrev_b32_e32 v22, 16, v23
	v_and_b32_e32 v23, 0xffff0000, v23
	v_pk_add_f32 v[16:17], v[16:17], v[22:23]
	v_lshlrev_b32_e32 v22, 16, v24
	v_and_b32_e32 v23, 0xffff0000, v24
	v_pk_add_f32 v[10:11], v[10:11], v[22:23]
	v_lshlrev_b32_e32 v22, 16, v25
	v_and_b32_e32 v23, 0xffff0000, v25
	v_pk_add_f32 v[14:15], v[14:15], v[26:27]
	v_pk_add_f32 v[12:13], v[12:13], v[22:23]
.LBB0_173:
	v_cvt_pk_bf16_f32 v14, v14, v15
	v_cvt_pk_bf16_f32 v15, v16, v17
	v_cvt_pk_bf16_f32 v16, v10, v11
	s_nop 0
	v_cvt_pk_bf16_f32 v17, v12, v13
	global_store_dwordx4 v[18:19], v[14:17], off
	s_and_b64 vcc, exec, s[36:37]
	s_waitcnt vmcnt(2)
	v_mov_b32_e32 v10, v218
	v_mov_b32_e32 v11, v219
	v_mov_b32_e32 v12, v220
	v_mov_b32_e32 v13, v221
	v_lshlrev_b32_e32 v0, 16, v10
	v_and_b32_e32 v10, 0xffff0000, v10
	v_lshlrev_b32_e32 v14, 16, v11
	v_and_b32_e32 v11, 0xffff0000, v11
	v_lshlrev_b32_e32 v15, 16, v12
	v_and_b32_e32 v12, 0xffff0000, v12
	v_lshlrev_b32_e32 v16, 16, v13
	v_and_b32_e32 v13, 0xffff0000, v13
	v_mul_f32_e32 v0, 0xbfb8aa3b, v0
	v_mul_f32_e32 v10, 0xbfb8aa3b, v10
	v_mul_f32_e32 v14, 0xbfb8aa3b, v14
	v_mul_f32_e32 v11, 0xbfb8aa3b, v11
	v_mul_f32_e32 v15, 0xbfb8aa3b, v15
	v_mul_f32_e32 v12, 0xbfb8aa3b, v12
	v_mul_f32_e32 v16, 0xbfb8aa3b, v16
	v_mul_f32_e32 v13, 0xbfb8aa3b, v13
	v_exp_f32_e32 v0, v0
	v_exp_f32_e32 v10, v10
	v_exp_f32_e32 v14, v14
	v_exp_f32_e32 v11, v11
	v_exp_f32_e32 v15, v15
	v_exp_f32_e32 v12, v12
	v_exp_f32_e32 v16, v16
	v_exp_f32_e32 v13, v13
	v_add_f32_e32 v0, 1.0, v0
	v_add_f32_e32 v17, 1.0, v10
	v_add_f32_e32 v14, 1.0, v14
	v_add_f32_e32 v20, 1.0, v11
	v_add_f32_e32 v15, 1.0, v15
	v_add_f32_e32 v21, 1.0, v12
	v_add_f32_e32 v16, 1.0, v16
	v_add_f32_e32 v22, 1.0, v13
	v_rcp_f32_e32 v10, v0
	v_rcp_f32_e32 v11, v17
	v_rcp_f32_e32 v12, v14
	v_rcp_f32_e32 v13, v20
	v_rcp_f32_e32 v14, v15
	v_rcp_f32_e32 v15, v21
	v_rcp_f32_e32 v16, v16
	v_rcp_f32_e32 v17, v22
	v_pk_mul_f32 v[6:7], v[6:7], v[10:11]
	v_pk_mul_f32 v[8:9], v[8:9], v[12:13]
	v_pk_mul_f32 v[10:11], v[2:3], v[14:15]
	v_pk_mul_f32 v[2:3], v[4:5], v[16:17]
	s_cbranch_vccnz .LBB0_175
	s_waitcnt vmcnt(0)
	v_mov_b32_e32 v12, v226
	v_mov_b32_e32 v13, v227
	v_mov_b32_e32 v14, v228
	v_mov_b32_e32 v15, v229
	v_lshlrev_b32_e32 v4, 16, v12
	v_and_b32_e32 v5, 0xffff0000, v12
	v_pk_add_f32 v[6:7], v[6:7], v[4:5]
	v_lshlrev_b32_e32 v4, 16, v13
	v_and_b32_e32 v5, 0xffff0000, v13
	v_pk_add_f32 v[8:9], v[8:9], v[4:5]
	v_lshlrev_b32_e32 v4, 16, v14
	v_and_b32_e32 v5, 0xffff0000, v14
	v_pk_add_f32 v[10:11], v[10:11], v[4:5]
	v_lshlrev_b32_e32 v4, 16, v15
	v_and_b32_e32 v5, 0xffff0000, v15
	v_pk_add_f32 v[2:3], v[2:3], v[4:5]

; DI float bflo(unsigned w) { return __uint_as_float(w << 16); }
; DI float bfhi(unsigned w) { return __uint_as_float(w & 0xffff0000u); }
; DI unsigned cvtpk(float lo, float hi) { unsigned r; asm volatile("v_cvt_pk_bf16_f32 %0, %1, %2" : "=v"(r) : "v"(lo), "v"(hi)); return r; }
; #define LRU_LOAD_X(ch) do { _Pragma("unroll") for (int i_ = 0; i_ < 11; ++i_) { const int t_ = (ch) * 64 + 8 * tg - 3 + i_;            \
;         px[i_] = t_ >= 0 ? *(const unsigned*)(p.proj + (size_t)t_ * LDP + C_LX + c0 + 2 * c2) : 0u; } } while (0)
; DI void lru_unit(const PP& p, int l, int nb, int seg, int pass, char* lds, bool dummy = false) {
;     ...
;     const int ch0 = seg * SEGC, ch1 = ch0 + SEGC;
;     LRU_LOAD_X(ch0);
;     float hprev = 0.f, atot = 1.f;
;     const int sc_ = tid & 127, sg = tid >> 7;
;     if (pass == 2)
;         for (int j = 0; j < seg; ++j) hprev = p.lstate[((nb * NSEG + j) * 2 + 0) * 128 + sc_] * hprev + p.lstate[((nb * NSEG + j) * 2 + 1) * 128 + sc_];
;     u32x4 ply[2];
;     for (int ch = ch0; ch < ch1; ++ch) {
; #pragma unroll
;         for (int t = 0; t < 8; ++t) {
;             float u0 = cb[0], u1 = cb[1];
; #pragma unroll
;             for (int i = 0; i < 4; ++i) { u0 += cw[i][0] * bflo(px[t + i]); u1 += cw[i][1] * bfhi(px[t + i]); }
;             const int tok = 8 * tg + t;
;             *(unsigned*)(Us + tok * 136 + 2 * c2) = cvtpk(u0, u1);
;             *(f32x2*)(Uf + tok * 128 + 2 * c2) = (f32x2){u0, u1};
;         }
;         __syncthreads();
;         if (ch + 1 < ch1) LRU_LOAD_X(ch + 1);
.LBB0_209:
	s_waitcnt vmcnt(0)
	v_lshlrev_b32_e32 v2, 16, v127
	v_and_b32_e32 v3, 0xffff0000, v127
	v_lshlrev_b32_e32 v4, 16, v128
	v_and_b32_e32 v5, 0xffff0000, v128
	v_pk_fma_f32 v[2:3], v[100:101], v[2:3], v[108:109]
	v_lshlrev_b32_e32 v6, 16, v130
	v_and_b32_e32 v7, 0xffff0000, v130
	v_pk_fma_f32 v[2:3], v[102:103], v[4:5], v[2:3]
	v_lshlrev_b32_e32 v8, 16, v131
	v_and_b32_e32 v9, 0xffff0000, v131
	v_pk_fma_f32 v[2:3], v[104:105], v[6:7], v[2:3]
	v_pk_fma_f32 v[4:5], v[100:101], v[4:5], v[108:109]
	v_pk_fma_f32 v[2:3], v[106:107], v[8:9], v[2:3]
	v_pk_fma_f32 v[4:5], v[102:103], v[6:7], v[4:5]
	v_cvt_pk_bf16_f32 v10, v2, v3
	ds_write_b32 v145, v10
	ds_write_b64 v146, v[2:3] offset:17408
	v_lshlrev_b32_e32 v2, 16, v132
	v_and_b32_e32 v3, 0xffff0000, v132
	v_pk_fma_f32 v[4:5], v[104:105], v[8:9], v[4:5]
	v_pk_fma_f32 v[6:7], v[100:101], v[6:7], v[108:109]
	v_pk_fma_f32 v[4:5], v[106:107], v[2:3], v[4:5]
	v_pk_fma_f32 v[6:7], v[102:103], v[8:9], v[6:7]
	v_cvt_pk_bf16_f32 v10, v4, v5
	ds_write_b32 v136, v10
	ds_write_b64 v144, v[4:5] offset:17408
	v_lshlrev_b32_e32 v4, 16, v134
	v_and_b32_e32 v5, 0xffff0000, v134
	v_pk_fma_f32 v[6:7], v[104:105], v[2:3], v[6:7]
	v_pk_fma_f32 v[8:9], v[100:101], v[8:9], v[108:109]
	v_pk_fma_f32 v[6:7], v[106:107], v[4:5], v[6:7]
	v_pk_fma_f32 v[8:9], v[102:103], v[2:3], v[8:9]
	v_cvt_pk_bf16_f32 v10, v6, v7
	ds_write_b32 v136, v10 offset:272
	ds_write_b64 v143, v[6:7] offset:17408
	v_lshlrev_b32_e32 v6, 16, v135
	v_and_b32_e32 v7, 0xffff0000, v135
	v_pk_fma_f32 v[8:9], v[104:105], v[4:5], v[8:9]
	v_pk_fma_f32 v[2:3], v[100:101], v[2:3], v[108:109]
	v_pk_fma_f32 v[8:9], v[106:107], v[6:7], v[8:9]
	v_pk_fma_f32 v[2:3], v[102:103], v[4:5], v[2:3]
	v_cvt_pk_bf16_f32 v10, v8, v9
	ds_write_b32 v136, v10 offset:544
	ds_write_b64 v142, v[8:9] offset:17408
	v_lshlrev_b32_e32 v8, 16, v141
	v_and_b32_e32 v9, 0xffff0000, v141
	v_pk_fma_f32 v[2:3], v[104:105], v[6:7], v[2:3]
	v_pk_fma_f32 v[4:5], v[100:101], v[4:5], v[108:109]
	v_pk_fma_f32 v[2:3], v[106:107], v[8:9], v[2:3]
	v_pk_fma_f32 v[4:5], v[102:103], v[6:7], v[4:5]
	v_cvt_pk_bf16_f32 v10, v2, v3
	ds_write_b32 v136, v10 offset:816
	ds_write_b64 v140, v[2:3] offset:17408
	v_lshlrev_b32_e32 v2, 16, v147
	v_and_b32_e32 v3, 0xffff0000, v147
	v_pk_fma_f32 v[4:5], v[104:105], v[8:9], v[4:5]
	v_pk_fma_f32 v[6:7], v[100:101], v[6:7], v[108:109]
	v_pk_fma_f32 v[4:5], v[106:107], v[2:3], v[4:5]
	v_pk_fma_f32 v[6:7], v[102:103], v[8:9], v[6:7]
	v_cvt_pk_bf16_f32 v10, v4, v5
	ds_write_b32 v136, v10 offset:1088
	ds_write_b64 v139, v[4:5] offset:17408
	v_lshlrev_b32_e32 v4, 16, v148
	v_and_b32_e32 v5, 0xffff0000, v148
	v_pk_fma_f32 v[6:7], v[104:105], v[2:3], v[6:7]
	v_pk_fma_f32 v[8:9], v[100:101], v[8:9], v[108:109]
	v_pk_fma_f32 v[6:7], v[106:107], v[4:5], v[6:7]
	v_pk_fma_f32 v[2:3], v[102:103], v[2:3], v[8:9]
	v_cvt_pk_bf16_f32 v10, v6, v7
	ds_write_b32 v136, v10 offset:1360
	ds_write_b64 v138, v[6:7] offset:17408
	v_lshlrev_b32_e32 v6, 16, v149
	v_and_b32_e32 v7, 0xffff0000, v149
	v_pk_fma_f32 v[2:3], v[104:105], v[4:5], v[2:3]
	s_cmp_lt_u32 s10, s9
	v_pk_fma_f32 v[2:3], v[106:107], v[6:7], v[2:3]
	s_nop 0
	v_cvt_pk_bf16_f32 v4, v2, v3
	ds_write_b32 v136, v4 offset:1632
	ds_write_b64 v137, v[2:3] offset:17408
	s_waitcnt lgkmcnt(0)
	s_barrier
	s_cbranch_scc0 .LBB0_208
	v_add_u32_e32 v2, s8, v129
	s_lshl_b32 s22, s24, 1
	s_addk_i32 s22, 0x1800
	v_add_u32_e32 v5, s22, v0
	v_add_u32_e32 v4, 61, v2
	v_mad_u32_u24 v4, v4, s35, v5
	global_load_dword v127, v4, s[86:87]
	v_add_u32_e32 v4, 62, v2
	v_mad_u32_u24 v4, v4, s35, v5
	global_load_dword v128, v4, s[86:87]
	v_add_u32_e32 v4, 63, v2
	v_mad_u32_u24 v4, v4, s35, v5
	global_load_dword v130, v4, s[86:87]
	v_add_u32_e32 v4, 64, v2
	v_mad_u32_u24 v4, v4, s35, v5
	global_load_dword v131, v4, s[86:87]
	v_add_u32_e32 v4, 65, v2
	v_mad_u32_u24 v4, v4, s35, v5
	global_load_dword v132, v4, s[86:87]
	v_add_u32_e32 v4, 66, v2
	v_mad_u32_u24 v4, v4, s35, v5
	global_load_dword v134, v4, s[86:87]
	v_add_u32_e32 v4, 67, v2
	v_mad_u32_u24 v4, v4, s35, v5
	global_load_dword v135, v4, s[86:87]
	v_add_u32_e32 v4, 68, v2
	v_mad_u32_u24 v4, v4, s35, v5
	global_load_dword v141, v4, s[86:87]
	v_add_u32_e32 v4, 69, v2
	v_mad_u32_u24 v4, v4, s35, v5
	global_load_dword v147, v4, s[86:87]
	v_add_u32_e32 v4, 70, v2
	v_mad_u32_u24 v4, v4, s35, v5
	global_load_dword v148, v4, s[86:87]
	v_add_u32_e32 v4, 71, v2
	v_mad_u32_u24 v4, v4, s35, v5
	global_load_dword v149, v4, s[86:87]
	s_branch .LBB0_208

; DI float bflo(unsigned w) { return __uint_as_float(w << 16); }
; DI float bfhi(unsigned w) { return __uint_as_float(w & 0xffff0000u); }
; DI unsigned cvtpk(float lo, float hi) { unsigned r; asm volatile("v_cvt_pk_bf16_f32 %0, %1, %2" : "=v"(r) : "v"(lo), "v"(hi)); return r; }
; #define LRU_LOAD_X(ch) do { _Pragma("unroll") for (int i_ = 0; i_ < 11; ++i_) { const int t_ = (ch) * 64 + 8 * tg - 3 + i_;            \
;         px[i_] = t_ >= 0 ? *(const unsigned*)(p.proj + (size_t)t_ * LDP + C_LX + c0 + 2 * c2) : 0u; } } while (0)
; DI void lru_unit(const PP& p, int l, int nb, int seg, int pass, char* lds, bool dummy = false) {
;     ...
;     const int ch0 = seg * SEGC, ch1 = ch0 + SEGC;
;     LRU_LOAD_X(ch0);
;     float hprev = 0.f, atot = 1.f;
;     const int sc_ = tid & 127, sg = tid >> 7;
;     if (pass == 2)
;         for (int j = 0; j < seg; ++j) hprev = p.lstate[((nb * NSEG + j) * 2 + 0) * 128 + sc_] * hprev + p.lstate[((nb * NSEG + j) * 2 + 1) * 128 + sc_];
;     u32x4 ply[2];
;     for (int ch = ch0; ch < ch1; ++ch) {
; #pragma unroll
;         for (int t = 0; t < 8; ++t) {
;             float u0 = cb[0], u1 = cb[1];
; #pragma unroll
;             for (int i = 0; i < 4; ++i) { u0 += cw[i][0] * bflo(px[t + i]); u1 += cw[i][1] * bfhi(px[t + i]); }
;             const int tok = 8 * tg + t;
;             *(unsigned*)(Us + tok * 136 + 2 * c2) = cvtpk(u0, u1);
;             *(f32x2*)(Uf + tok * 128 + 2 * c2) = (f32x2){u0, u1};
;         }
;         __syncthreads();
;         if (ch + 1 < ch1) LRU_LOAD_X(ch + 1);
.LBB0_462:
	s_waitcnt vmcnt(0)
	v_lshlrev_b32_e32 v2, 16, v124
	v_and_b32_e32 v3, 0xffff0000, v124
	v_lshlrev_b32_e32 v4, 16, v125
	v_and_b32_e32 v5, 0xffff0000, v125
	v_pk_fma_f32 v[2:3], v[106:107], v[2:3], v[114:115]
	v_lshlrev_b32_e32 v6, 16, v127
	v_and_b32_e32 v7, 0xffff0000, v127
	v_pk_fma_f32 v[2:3], v[108:109], v[4:5], v[2:3]
	v_lshlrev_b32_e32 v8, 16, v128
	v_and_b32_e32 v9, 0xffff0000, v128
	v_pk_fma_f32 v[2:3], v[110:111], v[6:7], v[2:3]
	v_pk_fma_f32 v[4:5], v[106:107], v[4:5], v[114:115]
	v_pk_fma_f32 v[2:3], v[112:113], v[8:9], v[2:3]
	v_pk_fma_f32 v[4:5], v[108:109], v[6:7], v[4:5]
	v_cvt_pk_bf16_f32 v10, v2, v3
	ds_write_b32 v147, v10
	ds_write_b64 v148, v[2:3] offset:17408
	v_lshlrev_b32_e32 v2, 16, v129
	v_and_b32_e32 v3, 0xffff0000, v129
	v_pk_fma_f32 v[4:5], v[110:111], v[8:9], v[4:5]
	v_pk_fma_f32 v[6:7], v[106:107], v[6:7], v[114:115]
	v_pk_fma_f32 v[4:5], v[112:113], v[2:3], v[4:5]
	v_pk_fma_f32 v[6:7], v[108:109], v[8:9], v[6:7]
	v_cvt_pk_bf16_f32 v10, v4, v5
	ds_write_b32 v149, v10
	ds_write_b64 v150, v[4:5] offset:17408
	v_lshlrev_b32_e32 v4, 16, v130
	v_and_b32_e32 v5, 0xffff0000, v130
	v_pk_fma_f32 v[6:7], v[110:111], v[2:3], v[6:7]
	v_pk_fma_f32 v[8:9], v[106:107], v[8:9], v[114:115]
	v_pk_fma_f32 v[6:7], v[112:113], v[4:5], v[6:7]
	v_pk_fma_f32 v[8:9], v[108:109], v[2:3], v[8:9]
	v_cvt_pk_bf16_f32 v10, v6, v7
	ds_write_b32 v149, v10 offset:272
	ds_write_b64 v151, v[6:7] offset:17408
	v_lshlrev_b32_e32 v6, 16, v131
	v_and_b32_e32 v7, 0xffff0000, v131
	v_pk_fma_f32 v[8:9], v[110:111], v[4:5], v[8:9]
	v_pk_fma_f32 v[2:3], v[106:107], v[2:3], v[114:115]
	v_pk_fma_f32 v[8:9], v[112:113], v[6:7], v[8:9]
	v_pk_fma_f32 v[2:3], v[108:109], v[4:5], v[2:3]
	v_cvt_pk_bf16_f32 v10, v8, v9
	ds_write_b32 v149, v10 offset:544
	ds_write_b64 v152, v[8:9] offset:17408
	v_lshlrev_b32_e32 v8, 16, v132
	v_and_b32_e32 v9, 0xffff0000, v132
	v_pk_fma_f32 v[2:3], v[110:111], v[6:7], v[2:3]
	v_pk_fma_f32 v[4:5], v[106:107], v[4:5], v[114:115]
	v_pk_fma_f32 v[2:3], v[112:113], v[8:9], v[2:3]
	v_pk_fma_f32 v[4:5], v[108:109], v[6:7], v[4:5]
	v_cvt_pk_bf16_f32 v10, v2, v3
	ds_write_b32 v149, v10 offset:816
	ds_write_b64 v153, v[2:3] offset:17408
	v_lshlrev_b32_e32 v2, 16, v135
	v_and_b32_e32 v3, 0xffff0000, v135
	v_pk_fma_f32 v[4:5], v[110:111], v[8:9], v[4:5]
	v_pk_fma_f32 v[6:7], v[106:107], v[6:7], v[114:115]
	v_pk_fma_f32 v[4:5], v[112:113], v[2:3], v[4:5]
	v_pk_fma_f32 v[6:7], v[108:109], v[8:9], v[6:7]
	v_cvt_pk_bf16_f32 v10, v4, v5
	ds_write_b32 v149, v10 offset:1088
	ds_write_b64 v154, v[4:5] offset:17408
	v_lshlrev_b32_e32 v4, 16, v146
	v_and_b32_e32 v5, 0xffff0000, v146
	v_pk_fma_f32 v[6:7], v[110:111], v[2:3], v[6:7]
	v_pk_fma_f32 v[8:9], v[106:107], v[8:9], v[114:115]
	v_pk_fma_f32 v[6:7], v[112:113], v[4:5], v[6:7]
	v_pk_fma_f32 v[2:3], v[108:109], v[2:3], v[8:9]
	v_cvt_pk_bf16_f32 v10, v6, v7
	ds_write_b32 v149, v10 offset:1360
	ds_write_b64 v155, v[6:7] offset:17408
	v_lshlrev_b32_e32 v6, 16, v161
	v_and_b32_e32 v7, 0xffff0000, v161
	v_pk_fma_f32 v[2:3], v[110:111], v[4:5], v[2:3]
	s_cmp_ge_u32 s6, s5
	v_pk_fma_f32 v[2:3], v[112:113], v[6:7], v[2:3]
	s_nop 0
	v_cvt_pk_bf16_f32 v4, v2, v3
	ds_write_b32 v149, v4 offset:1632
	ds_write_b64 v156, v[2:3] offset:17408
	s_waitcnt lgkmcnt(0)
	s_barrier
	s_cbranch_scc1 .LBB0_461
	v_add_u32_e32 v2, s4, v126
	s_lshl_b32 s10, s22, 1
	s_addk_i32 s10, 0x1800
	v_add_u32_e32 v5, s10, v0
	v_add_u32_e32 v4, 61, v2
	v_mad_u32_u24 v4, v4, s35, v5
	global_load_dword v124, v4, s[86:87]
	v_add_u32_e32 v4, 62, v2
	v_mad_u32_u24 v4, v4, s35, v5
	global_load_dword v125, v4, s[86:87]
	v_add_u32_e32 v4, 63, v2
	v_mad_u32_u24 v4, v4, s35, v5
	global_load_dword v127, v4, s[86:87]
	v_add_u32_e32 v4, 64, v2
	v_mad_u32_u24 v4, v4, s35, v5
	global_load_dword v128, v4, s[86:87]
	v_add_u32_e32 v4, 65, v2
	v_mad_u32_u24 v4, v4, s35, v5
	global_load_dword v129, v4, s[86:87]
	v_add_u32_e32 v4, 66, v2
	v_mad_u32_u24 v4, v4, s35, v5
	global_load_dword v130, v4, s[86:87]
	v_add_u32_e32 v4, 67, v2
	v_mad_u32_u24 v4, v4, s35, v5
	global_load_dword v131, v4, s[86:87]
	v_add_u32_e32 v4, 68, v2
	v_mad_u32_u24 v4, v4, s35, v5
	global_load_dword v132, v4, s[86:87]
	v_add_u32_e32 v4, 69, v2
	v_mad_u32_u24 v4, v4, s35, v5
	global_load_dword v135, v4, s[86:87]
	v_add_u32_e32 v4, 70, v2
	v_mad_u32_u24 v4, v4, s35, v5
	global_load_dword v146, v4, s[86:87]
	v_add_u32_e32 v4, 71, v2
	v_mad_u32_u24 v4, v4, s35, v5
	global_load_dword v161, v4, s[86:87]
	s_branch .LBB0_461
